# non-temporal hint on attention query loads and on the 8-bit gate stores/loads
# baseline (speedup 1.0000x reference)
; __device__ __forceinline__ unsigned cvt_pk_bf16(float lo, float hi) { f32x2c v = {lo, hi}; bf16x2c b = __builtin_convertvector(v, bf16x2c); return __builtin_bit_cast(unsigned, b); }
; __device__ __forceinline__ float sigm(float x) { return __builtin_amdgcn_rcpf(1.0f + __builtin_amdgcn_exp2f(-x * EPI_LOG2E)); }
; __device__ __forceinline__ f32x4 sigm4(f32x4 v) { return (f32x4){sigm(v[0]), sigm(v[1]), sigm(v[2]), sigm(v[3])}; }
; __device__ __forceinline__ u32x4 pack8(f32x4 v0, f32x4 v1) { u32x4 w; w.x = cvt_pk_bf16(v0[0], v0[1]); w.y = cvt_pk_bf16(v0[2], v0[3]); w.z = cvt_pk_bf16(v1[0], v1[1]); w.w = cvt_pk_bf16(v1[2], v1[3]); return w; }
; __device__ __forceinline__ f32x4 bf_lo4(unsigned a, unsigned b) { return (f32x4){__uint_as_float(a << 16), __uint_as_float(a & 0xffff0000u), __uint_as_float(b << 16), __uint_as_float(b & 0xffff0000u)}; }
; __device__ __forceinline__ unsigned q4u8(f32x4 g) { f32x4 t = g * 255.0f + 0.5f; t[0] = fmaxf(t[0], 1.0f); t[1] = fmaxf(t[1], 1.0f); t[2] = fmaxf(t[2], 1.0f); t[3] = fmaxf(t[3], 1.0f);     return (unsigned)t[0] | ((unsigned)t[1] << 8) | ((unsigned)t[2] << 16) | ((unsigned)t[3] << 24); }
;     __device__ __forceinline__ void operator()(const f32x4 (&acc)[2][2][4][2], const Unit& u, int wr, int wc, int fr, int fq) const {
;     ...
;         if (u.pn >= 14) {
;             const int col0 = (u.pn - 14) * 256 + 64 * wc + 8 * fq;
; #pragma unroll
;             for (int ai = 0; ai < 2; ++ai) if (ai < u.nai)
; #pragma unroll
;                 for (int m = 0; m < 4; ++m) { unsigned char* rowp = (unsigned char*)G + (size_t)(row0 + ai * HALF + m * 16) * 3072 + col0;
; #pragma unroll
;                     for (int bj = 0; bj < 2; ++bj) { typedef unsigned u32x2q __attribute__((ext_vector_type(2))); u32x2q w; w.x = q4u8(sigm4(acc[ai][bj][m][0])); w.y = q4u8(sigm4(acc[ai][bj][m][1])); *(u32x2q*)(rowp + 32 * bj) = w; } }
.LBB0_540:
	s_andn2_b64 vcc, exec, s[4:5]
	s_cbranch_vccnz .LBB0_543
	v_mul_f32_e32 v3, 0xbfb8aa3b, v128
	v_exp_f32_e32 v3, v3
	v_mul_f32_e32 v128, 0xbfb8aa3b, v129
	v_exp_f32_e32 v133, v128
	v_mul_f32_e32 v130, 0xbfb8aa3b, v130
	v_exp_f32_e32 v130, v130
	v_mul_f32_e32 v131, 0xbfb8aa3b, v131
	v_exp_f32_e32 v131, v131
	v_add_f32_e32 v3, 1.0, v3
	v_rcp_f32_e32 v132, v3
	v_add_f32_e32 v3, 1.0, v133
	v_rcp_f32_e32 v133, v3
	v_add_f32_e32 v3, 1.0, v130
	v_rcp_f32_e32 v130, v3
	v_add_f32_e32 v3, 1.0, v131
	v_mul_f32_e32 v124, 0xbfb8aa3b, v124
	v_mul_f32_e32 v125, 0xbfb8aa3b, v125
	v_rcp_f32_e32 v131, v3
	v_exp_f32_e32 v124, v124
	v_exp_f32_e32 v125, v125
	s_mov_b32 s4, 0x437f0000
	v_pk_fma_f32 v[132:133], v[132:133], s[4:5], 0.5 op_sel_hi:[1,0,0]
	v_mul_f32_e32 v126, 0xbfb8aa3b, v126
	v_mul_f32_e32 v127, 0xbfb8aa3b, v127
	v_pk_fma_f32 v[130:131], v[130:131], s[4:5], 0.5 op_sel_hi:[1,0,0]
	v_max_f32_e32 v3, 1.0, v132
	v_max_f32_e32 v132, 1.0, v133
	v_add_f32_e32 v124, 1.0, v124
	v_exp_f32_e32 v126, v126
	v_exp_f32_e32 v127, v127
	v_add_f32_e32 v125, 1.0, v125
	v_max_f32_e32 v130, 1.0, v130
	v_max_f32_e32 v131, 1.0, v131
	v_cvt_u32_f32_e32 v3, v3
	v_cvt_u32_f32_e32 v132, v132
	v_rcp_f32_e32 v124, v124
	v_rcp_f32_e32 v125, v125
	v_cvt_u32_f32_sdwa v130, v130 dst_sel:WORD_1 dst_unused:UNUSED_PAD src0_sel:DWORD
	v_cvt_u32_f32_sdwa v131, v131 dst_sel:BYTE_3 dst_unused:UNUSED_PAD src0_sel:DWORD
	v_add_f32_e32 v126, 1.0, v126
	v_add_f32_e32 v127, 1.0, v127
	v_mul_f32_e32 v120, 0xbfb8aa3b, v120
	v_mul_f32_e32 v121, 0xbfb8aa3b, v121
	v_rcp_f32_e32 v126, v126
	v_rcp_f32_e32 v127, v127
	v_lshl_or_b32 v3, v132, 8, v3
	v_pk_fma_f32 v[124:125], v[124:125], s[4:5], 0.5 op_sel_hi:[1,0,0]
	v_exp_f32_e32 v120, v120
	v_exp_f32_e32 v121, v121
	v_mul_f32_e32 v122, 0xbfb8aa3b, v122
	v_mul_f32_e32 v123, 0xbfb8aa3b, v123
	v_mul_f32_e32 v116, 0xbfb8aa3b, v116
	v_mul_f32_e32 v117, 0xbfb8aa3b, v117
	v_or3_b32 v130, v3, v130, v131
	v_max_f32_e32 v3, 1.0, v124
	v_max_f32_e32 v124, 1.0, v125
	v_exp_f32_e32 v122, v122
	v_exp_f32_e32 v123, v123
	v_exp_f32_e32 v116, v116
	v_exp_f32_e32 v117, v117
	v_mul_f32_e32 v118, 0xbfb8aa3b, v118
	v_mul_f32_e32 v119, 0xbfb8aa3b, v119
	v_cvt_u32_f32_e32 v3, v3
	v_cvt_u32_f32_e32 v124, v124
	v_exp_f32_e32 v118, v118
	v_exp_f32_e32 v119, v119
	v_pk_fma_f32 v[126:127], v[126:127], s[4:5], 0.5 op_sel_hi:[1,0,0]
	v_add_f32_e32 v120, 1.0, v120
	v_add_f32_e32 v121, 1.0, v121
	v_max_f32_e32 v125, 1.0, v126
	v_max_f32_e32 v126, 1.0, v127
	v_rcp_f32_e32 v120, v120
	v_add_f32_e32 v122, 1.0, v122
	v_add_f32_e32 v123, 1.0, v123
	v_rcp_f32_e32 v121, v121
	v_add_f32_e32 v116, 1.0, v116
	v_add_f32_e32 v117, 1.0, v117
	v_lshl_or_b32 v3, v124, 8, v3
	v_cvt_u32_f32_sdwa v124, v125 dst_sel:WORD_1 dst_unused:UNUSED_PAD src0_sel:DWORD
	v_cvt_u32_f32_sdwa v125, v126 dst_sel:BYTE_3 dst_unused:UNUSED_PAD src0_sel:DWORD
	v_rcp_f32_e32 v122, v122
	v_rcp_f32_e32 v123, v123
	v_rcp_f32_e32 v116, v116
	v_add_f32_e32 v118, 1.0, v118
	v_add_f32_e32 v119, 1.0, v119
	v_rcp_f32_e32 v117, v117
	v_rcp_f32_e32 v118, v118
	v_rcp_f32_e32 v119, v119
	v_pk_fma_f32 v[120:121], v[120:121], s[4:5], 0.5 op_sel_hi:[1,0,0]
	v_or3_b32 v131, v3, v124, v125
	v_pk_fma_f32 v[122:123], v[122:123], s[4:5], 0.5 op_sel_hi:[1,0,0]
	v_max_f32_e32 v3, 1.0, v120
	v_max_f32_e32 v120, 1.0, v121
	v_pk_fma_f32 v[116:117], v[116:117], s[4:5], 0.5 op_sel_hi:[1,0,0]
	v_max_f32_e32 v121, 1.0, v122
	v_max_f32_e32 v122, 1.0, v123
	v_cvt_u32_f32_e32 v3, v3
	v_cvt_u32_f32_e32 v120, v120
	v_pk_fma_f32 v[118:119], v[118:119], s[4:5], 0.5 op_sel_hi:[1,0,0]
	v_max_f32_e32 v116, 1.0, v116
	v_max_f32_e32 v117, 1.0, v117
	v_cvt_u32_f32_sdwa v121, v121 dst_sel:WORD_1 dst_unused:UNUSED_PAD src0_sel:DWORD
	v_cvt_u32_f32_sdwa v122, v122 dst_sel:BYTE_3 dst_unused:UNUSED_PAD src0_sel:DWORD
	v_max_f32_e32 v118, 1.0, v118
	v_max_f32_e32 v119, 1.0, v119
	v_cvt_u32_f32_e32 v123, v116
	v_cvt_u32_f32_e32 v117, v117
	v_cvt_u32_f32_sdwa v118, v118 dst_sel:WORD_1 dst_unused:UNUSED_PAD src0_sel:DWORD
	v_cvt_u32_f32_sdwa v119, v119 dst_sel:BYTE_3 dst_unused:UNUSED_PAD src0_sel:DWORD
	v_lshl_or_b32 v3, v120, 8, v3
	v_or3_b32 v116, v3, v121, v122
	v_lshl_or_b32 v3, v117, 8, v123
	v_or3_b32 v117, v3, v118, v119
	v_mul_f32_e32 v3, 0xbfb8aa3b, v112
	v_exp_f32_e32 v3, v3
	v_mul_f32_e32 v112, 0xbfb8aa3b, v113
	v_exp_f32_e32 v113, v112
	v_mul_f32_e32 v108, 0xbfb8aa3b, v108
	v_add_f32_e32 v3, 1.0, v3
	v_rcp_f32_e32 v112, v3
	v_add_f32_e32 v3, 1.0, v113
	v_mul_f32_e32 v113, 0xbfb8aa3b, v114
	v_exp_f32_e32 v114, v113
	v_mul_f32_e32 v113, 0xbfb8aa3b, v115
	v_exp_f32_e32 v115, v113
	v_rcp_f32_e32 v113, v3
	v_add_f32_e32 v3, 1.0, v114
	v_rcp_f32_e32 v114, v3
	v_add_f32_e32 v3, 1.0, v115
	v_mul_f32_e32 v109, 0xbfb8aa3b, v109
	v_rcp_f32_e32 v115, v3
	v_exp_f32_e32 v108, v108
	v_exp_f32_e32 v109, v109
	v_pk_fma_f32 v[112:113], v[112:113], s[4:5], 0.5 op_sel_hi:[1,0,0]
	v_mul_f32_e32 v110, 0xbfb8aa3b, v110
	v_mul_f32_e32 v111, 0xbfb8aa3b, v111
	v_pk_fma_f32 v[114:115], v[114:115], s[4:5], 0.5 op_sel_hi:[1,0,0]
	v_max_f32_e32 v3, 1.0, v112
	v_max_f32_e32 v112, 1.0, v113
	v_add_f32_e32 v108, 1.0, v108
	v_exp_f32_e32 v110, v110
	v_exp_f32_e32 v111, v111
	v_add_f32_e32 v109, 1.0, v109
	v_max_f32_e32 v113, 1.0, v114
	v_max_f32_e32 v114, 1.0, v115
	v_cvt_u32_f32_e32 v3, v3
	v_cvt_u32_f32_e32 v112, v112
	v_rcp_f32_e32 v108, v108
	v_rcp_f32_e32 v109, v109
	v_cvt_u32_f32_sdwa v113, v113 dst_sel:WORD_1 dst_unused:UNUSED_PAD src0_sel:DWORD
	v_cvt_u32_f32_sdwa v114, v114 dst_sel:BYTE_3 dst_unused:UNUSED_PAD src0_sel:DWORD
	v_add_f32_e32 v110, 1.0, v110
	v_add_f32_e32 v111, 1.0, v111
	v_mul_f32_e32 v104, 0xbfb8aa3b, v104
	v_mul_f32_e32 v105, 0xbfb8aa3b, v105
; __device__ __forceinline__ unsigned cvt_pk_bf16(float lo, float hi) { f32x2c v = {lo, hi}; bf16x2c b = __builtin_convertvector(v, bf16x2c); return __builtin_bit_cast(unsigned, b); }
; __device__ __forceinline__ float sigm(float x) { return __builtin_amdgcn_rcpf(1.0f + __builtin_amdgcn_exp2f(-x * EPI_LOG2E)); }
; __device__ __forceinline__ f32x4 sigm4(f32x4 v) { return (f32x4){sigm(v[0]), sigm(v[1]), sigm(v[2]), sigm(v[3])}; }
; __device__ __forceinline__ u32x4 pack8(f32x4 v0, f32x4 v1) { u32x4 w; w.x = cvt_pk_bf16(v0[0], v0[1]); w.y = cvt_pk_bf16(v0[2], v0[3]); w.z = cvt_pk_bf16(v1[0], v1[1]); w.w = cvt_pk_bf16(v1[2], v1[3]); return w; }
; __device__ __forceinline__ f32x4 bf_lo4(unsigned a, unsigned b) { return (f32x4){__uint_as_float(a << 16), __uint_as_float(a & 0xffff0000u), __uint_as_float(b << 16), __uint_as_float(b & 0xffff0000u)}; }
; __device__ __forceinline__ unsigned q4u8(f32x4 g) { f32x4 t = g * 255.0f + 0.5f; t[0] = fmaxf(t[0], 1.0f); t[1] = fmaxf(t[1], 1.0f); t[2] = fmaxf(t[2], 1.0f); t[3] = fmaxf(t[3], 1.0f);     return (unsigned)t[0] | ((unsigned)t[1] << 8) | ((unsigned)t[2] << 16) | ((unsigned)t[3] << 24); }
;     __device__ __forceinline__ void operator()(const f32x4 (&acc)[2][2][4][2], const Unit& u, int wr, int wc, int fr, int fq) const {
;     ...
;                     for (int bj = 0; bj < 2; ++bj) { typedef unsigned u32x2q __attribute__((ext_vector_type(2))); u32x2q w; w.x = q4u8(sigm4(acc[ai][bj][m][0])); w.y = q4u8(sigm4(acc[ai][bj][m][1])); *(u32x2q*)(rowp + 32 * bj) = w; } }
	v_rcp_f32_e32 v110, v110
	v_rcp_f32_e32 v111, v111
	v_lshl_or_b32 v3, v112, 8, v3
	v_pk_fma_f32 v[108:109], v[108:109], s[4:5], 0.5 op_sel_hi:[1,0,0]
	v_exp_f32_e32 v104, v104
	v_exp_f32_e32 v105, v105
	v_mul_f32_e32 v106, 0xbfb8aa3b, v106
	v_mul_f32_e32 v107, 0xbfb8aa3b, v107
	v_mul_f32_e32 v100, 0xbfb8aa3b, v100
	v_mul_f32_e32 v101, 0xbfb8aa3b, v101
	v_or3_b32 v112, v3, v113, v114
	v_max_f32_e32 v3, 1.0, v108
	v_max_f32_e32 v108, 1.0, v109
	v_exp_f32_e32 v106, v106
	v_exp_f32_e32 v107, v107
	v_exp_f32_e32 v100, v100
	v_exp_f32_e32 v101, v101
	v_mul_f32_e32 v102, 0xbfb8aa3b, v102
	v_mul_f32_e32 v103, 0xbfb8aa3b, v103
	v_cvt_u32_f32_e32 v3, v3
	v_cvt_u32_f32_e32 v108, v108
	v_exp_f32_e32 v102, v102
	v_exp_f32_e32 v103, v103
	v_pk_fma_f32 v[110:111], v[110:111], s[4:5], 0.5 op_sel_hi:[1,0,0]
	v_add_f32_e32 v104, 1.0, v104
	v_add_f32_e32 v105, 1.0, v105
	v_max_f32_e32 v109, 1.0, v110
	v_max_f32_e32 v110, 1.0, v111
	v_rcp_f32_e32 v104, v104
	v_add_f32_e32 v106, 1.0, v106
	v_add_f32_e32 v107, 1.0, v107
	v_rcp_f32_e32 v105, v105
	v_add_f32_e32 v100, 1.0, v100
	v_add_f32_e32 v101, 1.0, v101
	v_lshl_or_b32 v3, v108, 8, v3
	v_cvt_u32_f32_sdwa v108, v109 dst_sel:WORD_1 dst_unused:UNUSED_PAD src0_sel:DWORD
	v_cvt_u32_f32_sdwa v109, v110 dst_sel:BYTE_3 dst_unused:UNUSED_PAD src0_sel:DWORD
	v_rcp_f32_e32 v106, v106
	v_rcp_f32_e32 v107, v107
	v_rcp_f32_e32 v100, v100
	v_add_f32_e32 v102, 1.0, v102
	v_add_f32_e32 v103, 1.0, v103
	v_rcp_f32_e32 v101, v101
	v_rcp_f32_e32 v102, v102
	v_rcp_f32_e32 v103, v103
	v_pk_fma_f32 v[104:105], v[104:105], s[4:5], 0.5 op_sel_hi:[1,0,0]
	v_or3_b32 v113, v3, v108, v109
	v_pk_fma_f32 v[106:107], v[106:107], s[4:5], 0.5 op_sel_hi:[1,0,0]
	v_max_f32_e32 v3, 1.0, v104
	v_max_f32_e32 v104, 1.0, v105
	v_pk_fma_f32 v[100:101], v[100:101], s[4:5], 0.5 op_sel_hi:[1,0,0]
	v_max_f32_e32 v105, 1.0, v106
	v_max_f32_e32 v106, 1.0, v107
	v_cvt_u32_f32_e32 v3, v3
	v_cvt_u32_f32_e32 v104, v104
	v_pk_fma_f32 v[102:103], v[102:103], s[4:5], 0.5 op_sel_hi:[1,0,0]
	v_max_f32_e32 v100, 1.0, v100
	v_max_f32_e32 v101, 1.0, v101
	v_cvt_u32_f32_sdwa v105, v105 dst_sel:WORD_1 dst_unused:UNUSED_PAD src0_sel:DWORD
	v_cvt_u32_f32_sdwa v106, v106 dst_sel:BYTE_3 dst_unused:UNUSED_PAD src0_sel:DWORD
	v_max_f32_e32 v102, 1.0, v102
	v_max_f32_e32 v103, 1.0, v103
	v_cvt_u32_f32_e32 v107, v100
	v_cvt_u32_f32_e32 v101, v101
	v_cvt_u32_f32_sdwa v102, v102 dst_sel:WORD_1 dst_unused:UNUSED_PAD src0_sel:DWORD
	v_cvt_u32_f32_sdwa v103, v103 dst_sel:BYTE_3 dst_unused:UNUSED_PAD src0_sel:DWORD
	v_lshl_or_b32 v3, v104, 8, v3
	v_or3_b32 v100, v3, v105, v106
	v_lshl_or_b32 v3, v101, 8, v107
	v_or3_b32 v101, v3, v102, v103
	v_mul_f32_e32 v3, 0xbfb8aa3b, v96
	v_exp_f32_e32 v3, v3
	v_mul_f32_e32 v96, 0xbfb8aa3b, v97
	v_exp_f32_e32 v97, v96
	v_mul_f32_e32 v92, 0xbfb8aa3b, v92
	v_add_f32_e32 v3, 1.0, v3
	v_rcp_f32_e32 v96, v3
	v_add_f32_e32 v3, 1.0, v97
	v_mul_f32_e32 v97, 0xbfb8aa3b, v98
	v_exp_f32_e32 v98, v97
	v_mul_f32_e32 v97, 0xbfb8aa3b, v99
	v_exp_f32_e32 v99, v97
	v_rcp_f32_e32 v97, v3
	v_add_f32_e32 v3, 1.0, v98
	v_rcp_f32_e32 v98, v3
	v_add_f32_e32 v3, 1.0, v99
	v_mul_f32_e32 v93, 0xbfb8aa3b, v93
	v_rcp_f32_e32 v99, v3
	v_exp_f32_e32 v92, v92
	v_exp_f32_e32 v93, v93
	v_pk_fma_f32 v[96:97], v[96:97], s[4:5], 0.5 op_sel_hi:[1,0,0]
	v_mul_f32_e32 v94, 0xbfb8aa3b, v94
	v_mul_f32_e32 v95, 0xbfb8aa3b, v95
	v_pk_fma_f32 v[98:99], v[98:99], s[4:5], 0.5 op_sel_hi:[1,0,0]
	v_max_f32_e32 v3, 1.0, v96
	v_max_f32_e32 v96, 1.0, v97
	v_add_f32_e32 v92, 1.0, v92
	v_exp_f32_e32 v94, v94
	v_exp_f32_e32 v95, v95
	v_add_f32_e32 v93, 1.0, v93
	v_max_f32_e32 v97, 1.0, v98
	v_max_f32_e32 v98, 1.0, v99
	v_cvt_u32_f32_e32 v3, v3
	v_cvt_u32_f32_e32 v96, v96
	v_rcp_f32_e32 v92, v92
	v_rcp_f32_e32 v93, v93
	v_cvt_u32_f32_sdwa v97, v97 dst_sel:WORD_1 dst_unused:UNUSED_PAD src0_sel:DWORD
	v_cvt_u32_f32_sdwa v98, v98 dst_sel:BYTE_3 dst_unused:UNUSED_PAD src0_sel:DWORD
	v_add_f32_e32 v94, 1.0, v94
	v_add_f32_e32 v95, 1.0, v95
	v_mul_f32_e32 v88, 0xbfb8aa3b, v88
	v_mul_f32_e32 v89, 0xbfb8aa3b, v89
	v_rcp_f32_e32 v94, v94
	v_rcp_f32_e32 v95, v95
	v_lshl_or_b32 v3, v96, 8, v3
	v_pk_fma_f32 v[92:93], v[92:93], s[4:5], 0.5 op_sel_hi:[1,0,0]
	v_exp_f32_e32 v88, v88
	v_exp_f32_e32 v89, v89
	v_mul_f32_e32 v90, 0xbfb8aa3b, v90
	v_mul_f32_e32 v91, 0xbfb8aa3b, v91
	v_mul_f32_e32 v84, 0xbfb8aa3b, v84
	v_mul_f32_e32 v85, 0xbfb8aa3b, v85
	v_or3_b32 v96, v3, v97, v98
	v_max_f32_e32 v3, 1.0, v92
	v_max_f32_e32 v92, 1.0, v93
	v_exp_f32_e32 v90, v90
	v_exp_f32_e32 v91, v91
	v_exp_f32_e32 v84, v84
	v_exp_f32_e32 v85, v85
	v_mul_f32_e32 v86, 0xbfb8aa3b, v86
	v_mul_f32_e32 v87, 0xbfb8aa3b, v87
	v_cvt_u32_f32_e32 v3, v3
	v_cvt_u32_f32_e32 v92, v92
	v_exp_f32_e32 v86, v86
	v_exp_f32_e32 v87, v87
	v_pk_fma_f32 v[94:95], v[94:95], s[4:5], 0.5 op_sel_hi:[1,0,0]
	v_add_f32_e32 v88, 1.0, v88
	v_add_f32_e32 v89, 1.0, v89
	v_max_f32_e32 v93, 1.0, v94
	v_max_f32_e32 v94, 1.0, v95
	v_rcp_f32_e32 v88, v88
	v_add_f32_e32 v90, 1.0, v90
	v_add_f32_e32 v91, 1.0, v91
	v_rcp_f32_e32 v89, v89
	v_add_f32_e32 v84, 1.0, v84
	v_add_f32_e32 v85, 1.0, v85
	v_lshl_or_b32 v3, v92, 8, v3
	v_cvt_u32_f32_sdwa v92, v93 dst_sel:WORD_1 dst_unused:UNUSED_PAD src0_sel:DWORD
	v_cvt_u32_f32_sdwa v93, v94 dst_sel:BYTE_3 dst_unused:UNUSED_PAD src0_sel:DWORD
	v_rcp_f32_e32 v90, v90
	v_rcp_f32_e32 v91, v91
	v_rcp_f32_e32 v84, v84
	v_add_f32_e32 v86, 1.0, v86
	v_add_f32_e32 v87, 1.0, v87
	v_rcp_f32_e32 v85, v85
	v_rcp_f32_e32 v86, v86
	v_rcp_f32_e32 v87, v87
	v_pk_fma_f32 v[88:89], v[88:89], s[4:5], 0.5 op_sel_hi:[1,0,0]
	v_or3_b32 v97, v3, v92, v93
	v_pk_fma_f32 v[90:91], v[90:91], s[4:5], 0.5 op_sel_hi:[1,0,0]
	v_max_f32_e32 v3, 1.0, v88
; __device__ __forceinline__ f32x4 sigm4(f32x4 v) { return (f32x4){sigm(v[0]), sigm(v[1]), sigm(v[2]), sigm(v[3])}; }
; __device__ __forceinline__ unsigned q4u8(f32x4 g) { f32x4 t = g * 255.0f + 0.5f; t[0] = fmaxf(t[0], 1.0f); t[1] = fmaxf(t[1], 1.0f); t[2] = fmaxf(t[2], 1.0f); t[3] = fmaxf(t[3], 1.0f);     return (unsigned)t[0] | ((unsigned)t[1] << 8) | ((unsigned)t[2] << 16) | ((unsigned)t[3] << 24); }
;     __device__ __forceinline__ void operator()(const f32x4 (&acc)[2][2][4][2], const Unit& u, int wr, int wc, int fr, int fq) const {
;     ...
;             for (int ai = 0; ai < 2; ++ai) if (ai < u.nai)
; #pragma unroll
;                 for (int m = 0; m < 4; ++m) { unsigned char* rowp = (unsigned char*)G + (size_t)(row0 + ai * HALF + m * 16) * 3072 + col0;
; #pragma unroll
;                     for (int bj = 0; bj < 2; ++bj) { typedef unsigned u32x2q __attribute__((ext_vector_type(2))); u32x2q w; w.x = q4u8(sigm4(acc[ai][bj][m][0])); w.y = q4u8(sigm4(acc[ai][bj][m][1])); *(u32x2q*)(rowp + 32 * bj) = w; } }
	v_max_f32_e32 v88, 1.0, v89
	v_pk_fma_f32 v[84:85], v[84:85], s[4:5], 0.5 op_sel_hi:[1,0,0]
	v_max_f32_e32 v89, 1.0, v90
	v_max_f32_e32 v90, 1.0, v91
	v_cvt_u32_f32_e32 v3, v3
	v_cvt_u32_f32_e32 v88, v88
	v_pk_fma_f32 v[86:87], v[86:87], s[4:5], 0.5 op_sel_hi:[1,0,0]
	v_max_f32_e32 v84, 1.0, v84
	v_max_f32_e32 v85, 1.0, v85
	v_cvt_u32_f32_sdwa v89, v89 dst_sel:WORD_1 dst_unused:UNUSED_PAD src0_sel:DWORD
	v_cvt_u32_f32_sdwa v90, v90 dst_sel:BYTE_3 dst_unused:UNUSED_PAD src0_sel:DWORD
	v_max_f32_e32 v86, 1.0, v86
	v_max_f32_e32 v87, 1.0, v87
	v_cvt_u32_f32_e32 v91, v84
	v_cvt_u32_f32_e32 v85, v85
	v_cvt_u32_f32_sdwa v86, v86 dst_sel:WORD_1 dst_unused:UNUSED_PAD src0_sel:DWORD
	v_cvt_u32_f32_sdwa v87, v87 dst_sel:BYTE_3 dst_unused:UNUSED_PAD src0_sel:DWORD
	v_lshl_or_b32 v3, v88, 8, v3
	v_or3_b32 v84, v3, v89, v90
	v_lshl_or_b32 v3, v85, 8, v91
	v_or3_b32 v85, v3, v86, v87
	v_mul_f32_e32 v3, 0xbfb8aa3b, v80
	v_exp_f32_e32 v3, v3
	v_mul_f32_e32 v80, 0xbfb8aa3b, v81
	v_exp_f32_e32 v81, v80
	v_mul_f32_e32 v76, 0xbfb8aa3b, v76
	v_add_f32_e32 v3, 1.0, v3
	v_rcp_f32_e32 v80, v3
	v_add_f32_e32 v3, 1.0, v81
	v_mul_f32_e32 v81, 0xbfb8aa3b, v82
	v_exp_f32_e32 v82, v81
	v_mul_f32_e32 v81, 0xbfb8aa3b, v83
	v_exp_f32_e32 v83, v81
	v_rcp_f32_e32 v81, v3
	v_add_f32_e32 v3, 1.0, v82
	v_rcp_f32_e32 v82, v3
	v_add_f32_e32 v3, 1.0, v83
	v_mul_f32_e32 v77, 0xbfb8aa3b, v77
	v_rcp_f32_e32 v83, v3
	v_exp_f32_e32 v76, v76
	v_exp_f32_e32 v77, v77
	v_pk_fma_f32 v[80:81], v[80:81], s[4:5], 0.5 op_sel_hi:[1,0,0]
	v_mul_f32_e32 v78, 0xbfb8aa3b, v78
	v_mul_f32_e32 v79, 0xbfb8aa3b, v79
	v_pk_fma_f32 v[82:83], v[82:83], s[4:5], 0.5 op_sel_hi:[1,0,0]
	v_max_f32_e32 v3, 1.0, v80
	v_max_f32_e32 v80, 1.0, v81
	v_add_f32_e32 v76, 1.0, v76
	v_exp_f32_e32 v78, v78
	v_exp_f32_e32 v79, v79
	v_add_f32_e32 v77, 1.0, v77
	v_max_f32_e32 v81, 1.0, v82
	v_max_f32_e32 v82, 1.0, v83
	v_cvt_u32_f32_e32 v3, v3
	v_cvt_u32_f32_e32 v80, v80
	v_rcp_f32_e32 v76, v76
	v_rcp_f32_e32 v77, v77
	v_cvt_u32_f32_sdwa v81, v81 dst_sel:WORD_1 dst_unused:UNUSED_PAD src0_sel:DWORD
	v_cvt_u32_f32_sdwa v82, v82 dst_sel:BYTE_3 dst_unused:UNUSED_PAD src0_sel:DWORD
	v_add_f32_e32 v78, 1.0, v78
	v_add_f32_e32 v79, 1.0, v79
	v_mul_f32_e32 v72, 0xbfb8aa3b, v72
	v_mul_f32_e32 v73, 0xbfb8aa3b, v73
	v_rcp_f32_e32 v78, v78
	v_rcp_f32_e32 v79, v79
	v_lshl_or_b32 v3, v80, 8, v3
	v_pk_fma_f32 v[76:77], v[76:77], s[4:5], 0.5 op_sel_hi:[1,0,0]
	v_exp_f32_e32 v72, v72
	v_exp_f32_e32 v73, v73
	v_mul_f32_e32 v74, 0xbfb8aa3b, v74
	v_mul_f32_e32 v75, 0xbfb8aa3b, v75
	v_mul_f32_e32 v68, 0xbfb8aa3b, v68
	v_mul_f32_e32 v69, 0xbfb8aa3b, v69
	v_or3_b32 v80, v3, v81, v82
	v_max_f32_e32 v3, 1.0, v76
	v_max_f32_e32 v76, 1.0, v77
	v_exp_f32_e32 v74, v74
	v_exp_f32_e32 v75, v75
	v_exp_f32_e32 v68, v68
	v_exp_f32_e32 v69, v69
	v_mul_f32_e32 v70, 0xbfb8aa3b, v70
	v_mul_f32_e32 v71, 0xbfb8aa3b, v71
	v_cvt_u32_f32_e32 v3, v3
	v_cvt_u32_f32_e32 v76, v76
	v_exp_f32_e32 v70, v70
	v_exp_f32_e32 v71, v71
	v_pk_fma_f32 v[78:79], v[78:79], s[4:5], 0.5 op_sel_hi:[1,0,0]
	v_add_f32_e32 v72, 1.0, v72
	v_add_f32_e32 v73, 1.0, v73
	v_max_f32_e32 v77, 1.0, v78
	v_max_f32_e32 v78, 1.0, v79
	v_rcp_f32_e32 v72, v72
	v_add_f32_e32 v74, 1.0, v74
	v_add_f32_e32 v75, 1.0, v75
	v_rcp_f32_e32 v73, v73
	v_add_f32_e32 v68, 1.0, v68
	v_add_f32_e32 v69, 1.0, v69
	v_mov_b64_e32 v[128:129], s[10:11]
	v_lshl_or_b32 v3, v76, 8, v3
	v_cvt_u32_f32_sdwa v76, v77 dst_sel:WORD_1 dst_unused:UNUSED_PAD src0_sel:DWORD
	v_cvt_u32_f32_sdwa v77, v78 dst_sel:BYTE_3 dst_unused:UNUSED_PAD src0_sel:DWORD
	v_rcp_f32_e32 v74, v74
	v_rcp_f32_e32 v75, v75
	v_rcp_f32_e32 v68, v68
	v_add_f32_e32 v70, 1.0, v70
	v_add_f32_e32 v71, 1.0, v71
	v_rcp_f32_e32 v69, v69
	v_lshl_add_u32 v0, s26, 8, v223
	v_mad_i64_i32 v[134:135], s[0:1], v2, s19, v[128:129]
	v_rcp_f32_e32 v70, v70
	v_rcp_f32_e32 v71, v71
	v_lshl_add_u64 v[134:135], v[134:135], 0, v[0:1]
	global_store_dwordx2 v[134:135], v[116:117], off offset:32 nt
	v_add_u32_e32 v116, 16, v2
	v_pk_fma_f32 v[72:73], v[72:73], s[4:5], 0.5 op_sel_hi:[1,0,0]
	v_mad_i64_i32 v[116:117], s[0:1], v116, s19, v[128:129]
	v_or3_b32 v81, v3, v76, v77
	v_pk_fma_f32 v[74:75], v[74:75], s[4:5], 0.5 op_sel_hi:[1,0,0]
	v_max_f32_e32 v3, 1.0, v72
	v_max_f32_e32 v72, 1.0, v73
	v_pk_fma_f32 v[68:69], v[68:69], s[4:5], 0.5 op_sel_hi:[1,0,0]
	v_lshl_add_u64 v[116:117], v[116:117], 0, v[0:1]
	v_max_f32_e32 v73, 1.0, v74
	v_max_f32_e32 v74, 1.0, v75
	v_cvt_u32_f32_e32 v3, v3
	v_cvt_u32_f32_e32 v72, v72
	v_pk_fma_f32 v[70:71], v[70:71], s[4:5], 0.5 op_sel_hi:[1,0,0]
	v_max_f32_e32 v68, 1.0, v68
	v_max_f32_e32 v69, 1.0, v69
	global_store_dwordx2 v[116:117], v[100:101], off offset:32 nt
	v_add_u32_e32 v100, 32, v2
	v_cvt_u32_f32_sdwa v73, v73 dst_sel:WORD_1 dst_unused:UNUSED_PAD src0_sel:DWORD
	v_cvt_u32_f32_sdwa v74, v74 dst_sel:BYTE_3 dst_unused:UNUSED_PAD src0_sel:DWORD
	v_max_f32_e32 v70, 1.0, v70
	v_max_f32_e32 v71, 1.0, v71
	v_cvt_u32_f32_e32 v75, v68
	v_cvt_u32_f32_e32 v69, v69
	v_mad_i64_i32 v[100:101], s[0:1], v100, s19, v[128:129]
	v_cvt_u32_f32_sdwa v70, v70 dst_sel:WORD_1 dst_unused:UNUSED_PAD src0_sel:DWORD
	v_cvt_u32_f32_sdwa v71, v71 dst_sel:BYTE_3 dst_unused:UNUSED_PAD src0_sel:DWORD
	v_lshl_add_u64 v[100:101], v[100:101], 0, v[0:1]
	global_store_dwordx2 v[100:101], v[84:85], off offset:32 nt
	v_add_u32_e32 v84, 48, v2
	v_lshl_or_b32 v3, v72, 8, v3
	v_mad_i64_i32 v[84:85], s[0:1], v84, s19, v[128:129]
	v_or3_b32 v68, v3, v73, v74
	v_lshl_or_b32 v3, v69, 8, v75
	v_lshl_add_u64 v[84:85], v[84:85], 0, v[0:1]
	v_or3_b32 v69, v3, v70, v71
	s_cmp_eq_u32 s79, 1
	global_store_dwordx2 v[134:135], v[130:131], off nt
	global_store_dwordx2 v[116:117], v[112:113], off nt
	global_store_dwordx2 v[100:101], v[96:97], off nt
	global_store_dwordx2 v[84:85], v[80:81], off nt
	global_store_dwordx2 v[84:85], v[68:69], off offset:32 nt
	s_cbranch_scc1 .LBB0_543
; __device__ __forceinline__ unsigned cvt_pk_bf16(float lo, float hi) { f32x2c v = {lo, hi}; bf16x2c b = __builtin_convertvector(v, bf16x2c); return __builtin_bit_cast(unsigned, b); }
; __device__ __forceinline__ float sigm(float x) { return __builtin_amdgcn_rcpf(1.0f + __builtin_amdgcn_exp2f(-x * EPI_LOG2E)); }
; __device__ __forceinline__ f32x4 sigm4(f32x4 v) { return (f32x4){sigm(v[0]), sigm(v[1]), sigm(v[2]), sigm(v[3])}; }
; __device__ __forceinline__ u32x4 pack8(f32x4 v0, f32x4 v1) { u32x4 w; w.x = cvt_pk_bf16(v0[0], v0[1]); w.y = cvt_pk_bf16(v0[2], v0[3]); w.z = cvt_pk_bf16(v1[0], v1[1]); w.w = cvt_pk_bf16(v1[2], v1[3]); return w; }
; __device__ __forceinline__ f32x4 bf_lo4(unsigned a, unsigned b) { return (f32x4){__uint_as_float(a << 16), __uint_as_float(a & 0xffff0000u), __uint_as_float(b << 16), __uint_as_float(b & 0xffff0000u)}; }
; __device__ __forceinline__ unsigned q4u8(f32x4 g) { f32x4 t = g * 255.0f + 0.5f; t[0] = fmaxf(t[0], 1.0f); t[1] = fmaxf(t[1], 1.0f); t[2] = fmaxf(t[2], 1.0f); t[3] = fmaxf(t[3], 1.0f);     return (unsigned)t[0] | ((unsigned)t[1] << 8) | ((unsigned)t[2] << 16) | ((unsigned)t[3] << 24); }
;     __device__ __forceinline__ void operator()(const f32x4 (&acc)[2][2][4][2], const Unit& u, int wr, int wc, int fr, int fq) const {
;     ...
;             for (int ai = 0; ai < 2; ++ai) if (ai < u.nai)
; #pragma unroll
;                 for (int m = 0; m < 4; ++m) { unsigned char* rowp = (unsigned char*)G + (size_t)(row0 + ai * HALF + m * 16) * 3072 + col0;
; #pragma unroll
;                     for (int bj = 0; bj < 2; ++bj) { typedef unsigned u32x2q __attribute__((ext_vector_type(2))); u32x2q w; w.x = q4u8(sigm4(acc[ai][bj][m][0])); w.y = q4u8(sigm4(acc[ai][bj][m][1])); *(u32x2q*)(rowp + 32 * bj) = w; } }
	v_mul_f32_e32 v64, 0xbfb8aa3b, v64
	v_exp_f32_e32 v68, v64
	v_mul_f32_e32 v64, 0xbfb8aa3b, v65
	v_exp_f32_e32 v69, v64
	v_mul_f32_e32 v66, 0xbfb8aa3b, v66
	v_mul_f32_e32 v67, 0xbfb8aa3b, v67
	v_exp_f32_e32 v66, v66
	v_exp_f32_e32 v67, v67
	v_add_f32_e32 v68, 1.0, v68
	v_add_f32_e32 v69, 1.0, v69
	v_rcp_f32_e32 v68, v68
	v_rcp_f32_e32 v69, v69
	v_add_f32_e32 v66, 1.0, v66
	v_add_f32_e32 v67, 1.0, v67
	v_mul_f32_e32 v60, 0xbfb8aa3b, v60
	v_mul_f32_e32 v61, 0xbfb8aa3b, v61
	v_rcp_f32_e32 v66, v66
	v_rcp_f32_e32 v67, v67
	v_exp_f32_e32 v60, v60
	v_exp_f32_e32 v61, v61
	v_add_u32_e32 v3, 0x80, v2
	v_mov_b64_e32 v[64:65], s[10:11]
	v_pk_fma_f32 v[68:69], v[68:69], s[4:5], 0.5 op_sel_hi:[1,0,0]
	v_mul_f32_e32 v62, 0xbfb8aa3b, v62
	v_mul_f32_e32 v63, 0xbfb8aa3b, v63
	v_mad_i64_i32 v[70:71], s[0:1], v3, s19, v[64:65]
	v_pk_fma_f32 v[66:67], v[66:67], s[4:5], 0.5 op_sel_hi:[1,0,0]
	v_max_f32_e32 v3, 1.0, v68
	v_max_f32_e32 v68, 1.0, v69
	v_add_f32_e32 v60, 1.0, v60
	v_exp_f32_e32 v62, v62
	v_exp_f32_e32 v63, v63
	v_add_f32_e32 v61, 1.0, v61
	v_max_f32_e32 v66, 1.0, v66
	v_max_f32_e32 v67, 1.0, v67
	v_cvt_u32_f32_e32 v3, v3
	v_cvt_u32_f32_e32 v68, v68
	v_rcp_f32_e32 v60, v60
	v_rcp_f32_e32 v61, v61
	v_cvt_u32_f32_sdwa v66, v66 dst_sel:WORD_1 dst_unused:UNUSED_PAD src0_sel:DWORD
	v_cvt_u32_f32_sdwa v67, v67 dst_sel:BYTE_3 dst_unused:UNUSED_PAD src0_sel:DWORD
	v_add_f32_e32 v62, 1.0, v62
	v_add_f32_e32 v63, 1.0, v63
	v_mul_f32_e32 v56, 0xbfb8aa3b, v56
	v_mul_f32_e32 v57, 0xbfb8aa3b, v57
	v_rcp_f32_e32 v62, v62
	v_rcp_f32_e32 v63, v63
	v_lshl_or_b32 v3, v68, 8, v3
	v_pk_fma_f32 v[60:61], v[60:61], s[4:5], 0.5 op_sel_hi:[1,0,0]
	v_exp_f32_e32 v56, v56
	v_exp_f32_e32 v57, v57
	v_mul_f32_e32 v58, 0xbfb8aa3b, v58
	v_mul_f32_e32 v59, 0xbfb8aa3b, v59
	v_mul_f32_e32 v52, 0xbfb8aa3b, v52
	v_mul_f32_e32 v53, 0xbfb8aa3b, v53
	v_or3_b32 v66, v3, v66, v67
	v_max_f32_e32 v3, 1.0, v60
	v_max_f32_e32 v60, 1.0, v61
	v_exp_f32_e32 v58, v58
	v_exp_f32_e32 v59, v59
	v_exp_f32_e32 v52, v52
	v_exp_f32_e32 v53, v53
	v_mul_f32_e32 v54, 0xbfb8aa3b, v54
	v_mul_f32_e32 v55, 0xbfb8aa3b, v55
	v_cvt_u32_f32_e32 v3, v3
	v_cvt_u32_f32_e32 v60, v60
	v_exp_f32_e32 v54, v54
	v_exp_f32_e32 v55, v55
	v_pk_fma_f32 v[62:63], v[62:63], s[4:5], 0.5 op_sel_hi:[1,0,0]
	v_add_f32_e32 v56, 1.0, v56
	v_add_f32_e32 v57, 1.0, v57
	v_max_f32_e32 v61, 1.0, v62
	v_max_f32_e32 v62, 1.0, v63
	v_rcp_f32_e32 v56, v56
	v_add_f32_e32 v58, 1.0, v58
	v_add_f32_e32 v59, 1.0, v59
	v_rcp_f32_e32 v57, v57
	v_add_f32_e32 v52, 1.0, v52
	v_add_f32_e32 v53, 1.0, v53
	v_lshl_or_b32 v3, v60, 8, v3
	v_cvt_u32_f32_sdwa v60, v61 dst_sel:WORD_1 dst_unused:UNUSED_PAD src0_sel:DWORD
	v_cvt_u32_f32_sdwa v61, v62 dst_sel:BYTE_3 dst_unused:UNUSED_PAD src0_sel:DWORD
	v_rcp_f32_e32 v58, v58
	v_rcp_f32_e32 v59, v59
	v_rcp_f32_e32 v52, v52
	v_add_f32_e32 v54, 1.0, v54
	v_add_f32_e32 v55, 1.0, v55
	v_rcp_f32_e32 v53, v53
	v_rcp_f32_e32 v54, v54
	v_rcp_f32_e32 v55, v55
	v_pk_fma_f32 v[56:57], v[56:57], s[4:5], 0.5 op_sel_hi:[1,0,0]
	v_or3_b32 v67, v3, v60, v61
	v_pk_fma_f32 v[58:59], v[58:59], s[4:5], 0.5 op_sel_hi:[1,0,0]
	v_max_f32_e32 v3, 1.0, v56
	v_max_f32_e32 v56, 1.0, v57
	v_pk_fma_f32 v[52:53], v[52:53], s[4:5], 0.5 op_sel_hi:[1,0,0]
	v_max_f32_e32 v57, 1.0, v58
	v_max_f32_e32 v58, 1.0, v59
	v_cvt_u32_f32_e32 v3, v3
	v_cvt_u32_f32_e32 v56, v56
	v_pk_fma_f32 v[54:55], v[54:55], s[4:5], 0.5 op_sel_hi:[1,0,0]
	v_max_f32_e32 v52, 1.0, v52
	v_max_f32_e32 v53, 1.0, v53
	v_cvt_u32_f32_sdwa v57, v57 dst_sel:WORD_1 dst_unused:UNUSED_PAD src0_sel:DWORD
	v_cvt_u32_f32_sdwa v58, v58 dst_sel:BYTE_3 dst_unused:UNUSED_PAD src0_sel:DWORD
	v_max_f32_e32 v54, 1.0, v54
	v_max_f32_e32 v55, 1.0, v55
	v_cvt_u32_f32_e32 v59, v52
	v_cvt_u32_f32_e32 v53, v53
	v_cvt_u32_f32_sdwa v54, v54 dst_sel:WORD_1 dst_unused:UNUSED_PAD src0_sel:DWORD
	v_cvt_u32_f32_sdwa v55, v55 dst_sel:BYTE_3 dst_unused:UNUSED_PAD src0_sel:DWORD
	v_lshl_or_b32 v3, v56, 8, v3
	v_or3_b32 v52, v3, v57, v58
	v_lshl_or_b32 v3, v53, 8, v59
	v_or3_b32 v53, v3, v54, v55
	v_mul_f32_e32 v3, 0xbfb8aa3b, v48
	v_exp_f32_e32 v3, v3
	v_mul_f32_e32 v48, 0xbfb8aa3b, v49
	v_exp_f32_e32 v49, v48
	v_mul_f32_e32 v44, 0xbfb8aa3b, v44
	v_add_f32_e32 v3, 1.0, v3
	v_rcp_f32_e32 v48, v3
	v_add_f32_e32 v3, 1.0, v49
	v_mul_f32_e32 v49, 0xbfb8aa3b, v50
	v_exp_f32_e32 v50, v49
	v_mul_f32_e32 v49, 0xbfb8aa3b, v51
	v_exp_f32_e32 v51, v49
	v_rcp_f32_e32 v49, v3
	v_add_f32_e32 v3, 1.0, v50
	v_rcp_f32_e32 v50, v3
	v_add_f32_e32 v3, 1.0, v51
	v_mul_f32_e32 v45, 0xbfb8aa3b, v45
	v_rcp_f32_e32 v51, v3
	v_exp_f32_e32 v44, v44
	v_exp_f32_e32 v45, v45
	v_pk_fma_f32 v[48:49], v[48:49], s[4:5], 0.5 op_sel_hi:[1,0,0]
	v_mul_f32_e32 v46, 0xbfb8aa3b, v46
	v_mul_f32_e32 v47, 0xbfb8aa3b, v47
	v_pk_fma_f32 v[50:51], v[50:51], s[4:5], 0.5 op_sel_hi:[1,0,0]
	v_max_f32_e32 v3, 1.0, v48
	v_max_f32_e32 v48, 1.0, v49
	v_add_f32_e32 v44, 1.0, v44
	v_exp_f32_e32 v46, v46
	v_exp_f32_e32 v47, v47
	v_add_f32_e32 v45, 1.0, v45
	v_max_f32_e32 v49, 1.0, v50
	v_max_f32_e32 v50, 1.0, v51
	v_cvt_u32_f32_e32 v3, v3
	v_cvt_u32_f32_e32 v48, v48
	v_rcp_f32_e32 v44, v44
	v_rcp_f32_e32 v45, v45
	v_cvt_u32_f32_sdwa v49, v49 dst_sel:WORD_1 dst_unused:UNUSED_PAD src0_sel:DWORD
	v_cvt_u32_f32_sdwa v50, v50 dst_sel:BYTE_3 dst_unused:UNUSED_PAD src0_sel:DWORD
	v_add_f32_e32 v46, 1.0, v46
	v_add_f32_e32 v47, 1.0, v47
	v_mul_f32_e32 v40, 0xbfb8aa3b, v40
	v_mul_f32_e32 v41, 0xbfb8aa3b, v41
	v_rcp_f32_e32 v46, v46
	v_rcp_f32_e32 v47, v47
	v_lshl_or_b32 v3, v48, 8, v3
	v_pk_fma_f32 v[44:45], v[44:45], s[4:5], 0.5 op_sel_hi:[1,0,0]
	v_exp_f32_e32 v40, v40
	v_exp_f32_e32 v41, v41
	v_mul_f32_e32 v42, 0xbfb8aa3b, v42
	v_mul_f32_e32 v43, 0xbfb8aa3b, v43
; __device__ __forceinline__ unsigned cvt_pk_bf16(float lo, float hi) { f32x2c v = {lo, hi}; bf16x2c b = __builtin_convertvector(v, bf16x2c); return __builtin_bit_cast(unsigned, b); }
; __device__ __forceinline__ float sigm(float x) { return __builtin_amdgcn_rcpf(1.0f + __builtin_amdgcn_exp2f(-x * EPI_LOG2E)); }
; __device__ __forceinline__ f32x4 sigm4(f32x4 v) { return (f32x4){sigm(v[0]), sigm(v[1]), sigm(v[2]), sigm(v[3])}; }
; __device__ __forceinline__ u32x4 pack8(f32x4 v0, f32x4 v1) { u32x4 w; w.x = cvt_pk_bf16(v0[0], v0[1]); w.y = cvt_pk_bf16(v0[2], v0[3]); w.z = cvt_pk_bf16(v1[0], v1[1]); w.w = cvt_pk_bf16(v1[2], v1[3]); return w; }
; __device__ __forceinline__ f32x4 bf_lo4(unsigned a, unsigned b) { return (f32x4){__uint_as_float(a << 16), __uint_as_float(a & 0xffff0000u), __uint_as_float(b << 16), __uint_as_float(b & 0xffff0000u)}; }
; __device__ __forceinline__ unsigned q4u8(f32x4 g) { f32x4 t = g * 255.0f + 0.5f; t[0] = fmaxf(t[0], 1.0f); t[1] = fmaxf(t[1], 1.0f); t[2] = fmaxf(t[2], 1.0f); t[3] = fmaxf(t[3], 1.0f);     return (unsigned)t[0] | ((unsigned)t[1] << 8) | ((unsigned)t[2] << 16) | ((unsigned)t[3] << 24); }
;     __device__ __forceinline__ void operator()(const f32x4 (&acc)[2][2][4][2], const Unit& u, int wr, int wc, int fr, int fq) const {
;     ...
;                     for (int bj = 0; bj < 2; ++bj) { typedef unsigned u32x2q __attribute__((ext_vector_type(2))); u32x2q w; w.x = q4u8(sigm4(acc[ai][bj][m][0])); w.y = q4u8(sigm4(acc[ai][bj][m][1])); *(u32x2q*)(rowp + 32 * bj) = w; } }
	v_mul_f32_e32 v36, 0xbfb8aa3b, v36
	v_mul_f32_e32 v37, 0xbfb8aa3b, v37
	v_or3_b32 v48, v3, v49, v50
	v_max_f32_e32 v3, 1.0, v44
	v_max_f32_e32 v44, 1.0, v45
	v_exp_f32_e32 v42, v42
	v_exp_f32_e32 v43, v43
	v_exp_f32_e32 v36, v36
	v_exp_f32_e32 v37, v37
	v_mul_f32_e32 v38, 0xbfb8aa3b, v38
	v_mul_f32_e32 v39, 0xbfb8aa3b, v39
	v_cvt_u32_f32_e32 v3, v3
	v_cvt_u32_f32_e32 v44, v44
	v_exp_f32_e32 v38, v38
	v_exp_f32_e32 v39, v39
	v_pk_fma_f32 v[46:47], v[46:47], s[4:5], 0.5 op_sel_hi:[1,0,0]
	v_add_f32_e32 v40, 1.0, v40
	v_add_f32_e32 v41, 1.0, v41
	v_max_f32_e32 v45, 1.0, v46
	v_max_f32_e32 v46, 1.0, v47
	v_rcp_f32_e32 v40, v40
	v_add_f32_e32 v42, 1.0, v42
	v_add_f32_e32 v43, 1.0, v43
	v_rcp_f32_e32 v41, v41
	v_add_f32_e32 v36, 1.0, v36
	v_add_f32_e32 v37, 1.0, v37
	v_lshl_or_b32 v3, v44, 8, v3
	v_cvt_u32_f32_sdwa v44, v45 dst_sel:WORD_1 dst_unused:UNUSED_PAD src0_sel:DWORD
	v_cvt_u32_f32_sdwa v45, v46 dst_sel:BYTE_3 dst_unused:UNUSED_PAD src0_sel:DWORD
	v_rcp_f32_e32 v42, v42
	v_rcp_f32_e32 v43, v43
	v_rcp_f32_e32 v36, v36
	v_add_f32_e32 v38, 1.0, v38
	v_add_f32_e32 v39, 1.0, v39
	v_rcp_f32_e32 v37, v37
	v_rcp_f32_e32 v38, v38
	v_rcp_f32_e32 v39, v39
	v_pk_fma_f32 v[40:41], v[40:41], s[4:5], 0.5 op_sel_hi:[1,0,0]
	v_or3_b32 v49, v3, v44, v45
	v_pk_fma_f32 v[42:43], v[42:43], s[4:5], 0.5 op_sel_hi:[1,0,0]
	v_max_f32_e32 v3, 1.0, v40
	v_max_f32_e32 v40, 1.0, v41
	v_pk_fma_f32 v[36:37], v[36:37], s[4:5], 0.5 op_sel_hi:[1,0,0]
	v_max_f32_e32 v41, 1.0, v42
	v_max_f32_e32 v42, 1.0, v43
	v_cvt_u32_f32_e32 v3, v3
	v_cvt_u32_f32_e32 v40, v40
	v_pk_fma_f32 v[38:39], v[38:39], s[4:5], 0.5 op_sel_hi:[1,0,0]
	v_max_f32_e32 v36, 1.0, v36
	v_max_f32_e32 v37, 1.0, v37
	v_cvt_u32_f32_sdwa v41, v41 dst_sel:WORD_1 dst_unused:UNUSED_PAD src0_sel:DWORD
	v_cvt_u32_f32_sdwa v42, v42 dst_sel:BYTE_3 dst_unused:UNUSED_PAD src0_sel:DWORD
	v_max_f32_e32 v38, 1.0, v38
	v_max_f32_e32 v39, 1.0, v39
	v_cvt_u32_f32_e32 v43, v36
	v_cvt_u32_f32_e32 v37, v37
	v_cvt_u32_f32_sdwa v38, v38 dst_sel:WORD_1 dst_unused:UNUSED_PAD src0_sel:DWORD
	v_cvt_u32_f32_sdwa v39, v39 dst_sel:BYTE_3 dst_unused:UNUSED_PAD src0_sel:DWORD
	v_lshl_or_b32 v3, v40, 8, v3
	v_or3_b32 v36, v3, v41, v42
	v_lshl_or_b32 v3, v37, 8, v43
	v_or3_b32 v37, v3, v38, v39
	v_mul_f32_e32 v3, 0xbfb8aa3b, v32
	v_exp_f32_e32 v3, v3
	v_mul_f32_e32 v32, 0xbfb8aa3b, v33
	v_exp_f32_e32 v33, v32
	v_mul_f32_e32 v28, 0xbfb8aa3b, v28
	v_add_f32_e32 v3, 1.0, v3
	v_rcp_f32_e32 v32, v3
	v_add_f32_e32 v3, 1.0, v33
	v_mul_f32_e32 v33, 0xbfb8aa3b, v34
	v_exp_f32_e32 v34, v33
	v_mul_f32_e32 v33, 0xbfb8aa3b, v35
	v_exp_f32_e32 v35, v33
	v_rcp_f32_e32 v33, v3
	v_add_f32_e32 v3, 1.0, v34
	v_rcp_f32_e32 v34, v3
	v_add_f32_e32 v3, 1.0, v35
	v_mul_f32_e32 v29, 0xbfb8aa3b, v29
	v_rcp_f32_e32 v35, v3
	v_exp_f32_e32 v28, v28
	v_exp_f32_e32 v29, v29
	v_pk_fma_f32 v[32:33], v[32:33], s[4:5], 0.5 op_sel_hi:[1,0,0]
	v_mul_f32_e32 v30, 0xbfb8aa3b, v30
	v_mul_f32_e32 v31, 0xbfb8aa3b, v31
	v_pk_fma_f32 v[34:35], v[34:35], s[4:5], 0.5 op_sel_hi:[1,0,0]
	v_max_f32_e32 v3, 1.0, v32
	v_max_f32_e32 v32, 1.0, v33
	v_add_f32_e32 v28, 1.0, v28
	v_exp_f32_e32 v30, v30
	v_exp_f32_e32 v31, v31
	v_add_f32_e32 v29, 1.0, v29
	v_max_f32_e32 v33, 1.0, v34
	v_max_f32_e32 v34, 1.0, v35
	v_cvt_u32_f32_e32 v3, v3
	v_cvt_u32_f32_e32 v32, v32
	v_rcp_f32_e32 v28, v28
	v_rcp_f32_e32 v29, v29
	v_cvt_u32_f32_sdwa v33, v33 dst_sel:WORD_1 dst_unused:UNUSED_PAD src0_sel:DWORD
	v_cvt_u32_f32_sdwa v34, v34 dst_sel:BYTE_3 dst_unused:UNUSED_PAD src0_sel:DWORD
	v_add_f32_e32 v30, 1.0, v30
	v_add_f32_e32 v31, 1.0, v31
	v_mul_f32_e32 v24, 0xbfb8aa3b, v24
	v_mul_f32_e32 v25, 0xbfb8aa3b, v25
	v_rcp_f32_e32 v30, v30
	v_rcp_f32_e32 v31, v31
	v_lshl_or_b32 v3, v32, 8, v3
	v_pk_fma_f32 v[28:29], v[28:29], s[4:5], 0.5 op_sel_hi:[1,0,0]
	v_exp_f32_e32 v24, v24
	v_exp_f32_e32 v25, v25
	v_mul_f32_e32 v26, 0xbfb8aa3b, v26
	v_mul_f32_e32 v27, 0xbfb8aa3b, v27
	v_mul_f32_e32 v20, 0xbfb8aa3b, v20
	v_mul_f32_e32 v21, 0xbfb8aa3b, v21
	v_or3_b32 v32, v3, v33, v34
	v_max_f32_e32 v3, 1.0, v28
	v_max_f32_e32 v28, 1.0, v29
	v_exp_f32_e32 v26, v26
	v_exp_f32_e32 v27, v27
	v_exp_f32_e32 v20, v20
	v_exp_f32_e32 v21, v21
	v_mul_f32_e32 v22, 0xbfb8aa3b, v22
	v_mul_f32_e32 v23, 0xbfb8aa3b, v23
	v_cvt_u32_f32_e32 v3, v3
	v_cvt_u32_f32_e32 v28, v28
	v_exp_f32_e32 v22, v22
	v_exp_f32_e32 v23, v23
	v_pk_fma_f32 v[30:31], v[30:31], s[4:5], 0.5 op_sel_hi:[1,0,0]
	v_add_f32_e32 v24, 1.0, v24
	v_add_f32_e32 v25, 1.0, v25
	v_max_f32_e32 v29, 1.0, v30
	v_max_f32_e32 v30, 1.0, v31
	v_rcp_f32_e32 v24, v24
	v_add_f32_e32 v26, 1.0, v26
	v_add_f32_e32 v27, 1.0, v27
	v_rcp_f32_e32 v25, v25
	v_add_f32_e32 v20, 1.0, v20
	v_add_f32_e32 v21, 1.0, v21
	v_lshl_or_b32 v3, v28, 8, v3
	v_cvt_u32_f32_sdwa v28, v29 dst_sel:WORD_1 dst_unused:UNUSED_PAD src0_sel:DWORD
	v_cvt_u32_f32_sdwa v29, v30 dst_sel:BYTE_3 dst_unused:UNUSED_PAD src0_sel:DWORD
	v_rcp_f32_e32 v26, v26
	v_rcp_f32_e32 v27, v27
	v_rcp_f32_e32 v20, v20
	v_add_f32_e32 v22, 1.0, v22
	v_add_f32_e32 v23, 1.0, v23
	v_rcp_f32_e32 v21, v21
	v_rcp_f32_e32 v22, v22
	v_rcp_f32_e32 v23, v23
	v_pk_fma_f32 v[24:25], v[24:25], s[4:5], 0.5 op_sel_hi:[1,0,0]
	v_or3_b32 v33, v3, v28, v29
	v_pk_fma_f32 v[26:27], v[26:27], s[4:5], 0.5 op_sel_hi:[1,0,0]
	v_max_f32_e32 v3, 1.0, v24
	v_max_f32_e32 v24, 1.0, v25
	v_pk_fma_f32 v[20:21], v[20:21], s[4:5], 0.5 op_sel_hi:[1,0,0]
	v_max_f32_e32 v25, 1.0, v26
; __device__ __forceinline__ f32x4 sigm4(f32x4 v) { return (f32x4){sigm(v[0]), sigm(v[1]), sigm(v[2]), sigm(v[3])}; }
; __device__ __forceinline__ unsigned q4u8(f32x4 g) { f32x4 t = g * 255.0f + 0.5f; t[0] = fmaxf(t[0], 1.0f); t[1] = fmaxf(t[1], 1.0f); t[2] = fmaxf(t[2], 1.0f); t[3] = fmaxf(t[3], 1.0f);     return (unsigned)t[0] | ((unsigned)t[1] << 8) | ((unsigned)t[2] << 16) | ((unsigned)t[3] << 24); }
;     __device__ __forceinline__ void operator()(const f32x4 (&acc)[2][2][4][2], const Unit& u, int wr, int wc, int fr, int fq) const {
;     ...
;             for (int ai = 0; ai < 2; ++ai) if (ai < u.nai)
; #pragma unroll
;                 for (int m = 0; m < 4; ++m) { unsigned char* rowp = (unsigned char*)G + (size_t)(row0 + ai * HALF + m * 16) * 3072 + col0;
; #pragma unroll
;                     for (int bj = 0; bj < 2; ++bj) { typedef unsigned u32x2q __attribute__((ext_vector_type(2))); u32x2q w; w.x = q4u8(sigm4(acc[ai][bj][m][0])); w.y = q4u8(sigm4(acc[ai][bj][m][1])); *(u32x2q*)(rowp + 32 * bj) = w; } }
	v_max_f32_e32 v26, 1.0, v27
	v_cvt_u32_f32_e32 v3, v3
	v_cvt_u32_f32_e32 v24, v24
	v_pk_fma_f32 v[22:23], v[22:23], s[4:5], 0.5 op_sel_hi:[1,0,0]
	v_max_f32_e32 v20, 1.0, v20
	v_max_f32_e32 v21, 1.0, v21
	v_cvt_u32_f32_sdwa v25, v25 dst_sel:WORD_1 dst_unused:UNUSED_PAD src0_sel:DWORD
	v_cvt_u32_f32_sdwa v26, v26 dst_sel:BYTE_3 dst_unused:UNUSED_PAD src0_sel:DWORD
	v_max_f32_e32 v22, 1.0, v22
	v_max_f32_e32 v23, 1.0, v23
	v_cvt_u32_f32_e32 v27, v20
	v_cvt_u32_f32_e32 v21, v21
	v_cvt_u32_f32_sdwa v22, v22 dst_sel:WORD_1 dst_unused:UNUSED_PAD src0_sel:DWORD
	v_cvt_u32_f32_sdwa v23, v23 dst_sel:BYTE_3 dst_unused:UNUSED_PAD src0_sel:DWORD
	v_lshl_add_u64 v[70:71], v[70:71], 0, v[0:1]
	v_lshl_or_b32 v3, v24, 8, v3
	global_store_dwordx2 v[70:71], v[52:53], off offset:32 nt
	v_add_u32_e32 v52, 0x90, v2
	v_or3_b32 v20, v3, v25, v26
	v_lshl_or_b32 v3, v21, 8, v27
	v_mad_i64_i32 v[52:53], s[0:1], v52, s19, v[64:65]
	v_or3_b32 v21, v3, v22, v23
	v_mul_f32_e32 v3, 0xbfb8aa3b, v16
	v_mul_f32_e32 v16, 0xbfb8aa3b, v17
	v_lshl_add_u64 v[52:53], v[52:53], 0, v[0:1]
	v_exp_f32_e32 v3, v3
	v_exp_f32_e32 v16, v16
	global_store_dwordx2 v[52:53], v[36:37], off offset:32 nt
	v_add_u32_e32 v36, 0xa0, v2
	v_mad_i64_i32 v[36:37], s[0:1], v36, s19, v[64:65]
	v_lshl_add_u64 v[36:37], v[36:37], 0, v[0:1]
	global_store_dwordx2 v[36:37], v[20:21], off offset:32 nt
	v_add_u32_e32 v20, 0xb0, v2
	v_add_f32_e32 v2, 1.0, v3
	v_add_f32_e32 v3, 1.0, v16
	v_mul_f32_e32 v16, 0xbfb8aa3b, v18
	v_mul_f32_e32 v17, 0xbfb8aa3b, v19
	v_exp_f32_e32 v16, v16
	v_exp_f32_e32 v17, v17
	v_rcp_f32_e32 v2, v2
	v_rcp_f32_e32 v3, v3
	v_add_f32_e32 v16, 1.0, v16
	v_add_f32_e32 v17, 1.0, v17
	v_rcp_f32_e32 v16, v16
	v_rcp_f32_e32 v17, v17
	v_mul_f32_e32 v12, 0xbfb8aa3b, v12
	v_exp_f32_e32 v12, v12
	v_mad_i64_i32 v[18:19], s[0:1], v20, s19, v[64:65]
	v_pk_fma_f32 v[16:17], v[16:17], s[4:5], 0.5 op_sel_hi:[1,0,0]
	v_pk_fma_f32 v[2:3], v[2:3], s[4:5], 0.5 op_sel_hi:[1,0,0]
	v_lshl_add_u64 v[18:19], v[18:19], 0, v[0:1]
	v_max_f32_e32 v0, 1.0, v2
	v_max_f32_e32 v2, 1.0, v3
	v_max_f32_e32 v3, 1.0, v16
	v_max_f32_e32 v16, 1.0, v17
	v_cvt_u32_f32_e32 v17, v2
	v_cvt_u32_f32_sdwa v20, v3 dst_sel:WORD_1 dst_unused:UNUSED_PAD src0_sel:DWORD
	v_add_f32_e32 v2, 1.0, v12
	v_mul_f32_e32 v3, 0xbfb8aa3b, v13
	v_mul_f32_e32 v12, 0xbfb8aa3b, v14
	v_mul_f32_e32 v13, 0xbfb8aa3b, v15
	v_exp_f32_e32 v3, v3
	v_exp_f32_e32 v12, v12
	v_exp_f32_e32 v13, v13
	v_cvt_u32_f32_e32 v0, v0
	v_add_f32_e32 v3, 1.0, v3
	v_add_f32_e32 v12, 1.0, v12
	v_add_f32_e32 v13, 1.0, v13
	v_rcp_f32_e32 v2, v2
	v_rcp_f32_e32 v12, v12
	v_rcp_f32_e32 v13, v13
	v_rcp_f32_e32 v3, v3
	v_cvt_u32_f32_sdwa v16, v16 dst_sel:BYTE_3 dst_unused:UNUSED_PAD src0_sel:DWORD
	v_lshl_or_b32 v0, v17, 8, v0
	v_pk_fma_f32 v[12:13], v[12:13], s[4:5], 0.5 op_sel_hi:[1,0,0]
	v_pk_fma_f32 v[2:3], v[2:3], s[4:5], 0.5 op_sel_hi:[1,0,0]
	v_or3_b32 v14, v0, v20, v16
	v_max_f32_e32 v0, 1.0, v2
	v_max_f32_e32 v2, 1.0, v3
	v_max_f32_e32 v3, 1.0, v12
	v_max_f32_e32 v12, 1.0, v13
	v_mul_f32_e32 v8, 0xbfb8aa3b, v8
	v_cvt_u32_f32_sdwa v13, v3 dst_sel:WORD_1 dst_unused:UNUSED_PAD src0_sel:DWORD
	v_mul_f32_e32 v3, 0xbfb8aa3b, v9
	v_cvt_u32_f32_e32 v0, v0
	v_cvt_u32_f32_e32 v2, v2
	v_exp_f32_e32 v8, v8
	v_exp_f32_e32 v3, v3
	v_cvt_u32_f32_sdwa v12, v12 dst_sel:BYTE_3 dst_unused:UNUSED_PAD src0_sel:DWORD
	v_lshl_or_b32 v0, v2, 8, v0
	v_add_f32_e32 v2, 1.0, v8
	v_add_f32_e32 v3, 1.0, v3
	v_rcp_f32_e32 v2, v2
	v_rcp_f32_e32 v3, v3
	v_or3_b32 v15, v0, v13, v12
	v_mul_f32_e32 v8, 0xbfb8aa3b, v10
	v_mul_f32_e32 v9, 0xbfb8aa3b, v11
	v_pk_fma_f32 v[2:3], v[2:3], s[4:5], 0.5 op_sel_hi:[1,0,0]
	v_exp_f32_e32 v8, v8
	v_max_f32_e32 v0, 1.0, v2
	v_max_f32_e32 v2, 1.0, v3
	v_mul_f32_e32 v3, 0xbfb8aa3b, v4
	v_exp_f32_e32 v3, v3
	v_cvt_u32_f32_e32 v10, v2
	v_exp_f32_e32 v9, v9
	v_mul_f32_e32 v4, 0xbfb8aa3b, v6
	v_add_f32_e32 v2, 1.0, v3
	v_mul_f32_e32 v3, 0xbfb8aa3b, v5
	v_exp_f32_e32 v3, v3
	v_mul_f32_e32 v5, 0xbfb8aa3b, v7
	v_exp_f32_e32 v4, v4
	v_exp_f32_e32 v5, v5
	v_add_f32_e32 v8, 1.0, v8
	v_add_f32_e32 v9, 1.0, v9
	v_add_f32_e32 v3, 1.0, v3
	v_rcp_f32_e32 v8, v8
	v_rcp_f32_e32 v9, v9
	v_rcp_f32_e32 v2, v2
	v_add_f32_e32 v4, 1.0, v4
	v_add_f32_e32 v5, 1.0, v5
	v_rcp_f32_e32 v3, v3
	v_rcp_f32_e32 v4, v4
	v_rcp_f32_e32 v5, v5
	v_pk_fma_f32 v[8:9], v[8:9], s[4:5], 0.5 op_sel_hi:[1,0,0]
	v_pk_fma_f32 v[2:3], v[2:3], s[4:5], 0.5 op_sel_hi:[1,0,0]
	v_max_f32_e32 v8, 1.0, v8
	v_max_f32_e32 v9, 1.0, v9
	v_cvt_u32_f32_e32 v0, v0
	v_pk_fma_f32 v[4:5], v[4:5], s[4:5], 0.5 op_sel_hi:[1,0,0]
	v_max_f32_e32 v2, 1.0, v2
	v_max_f32_e32 v3, 1.0, v3
	v_cvt_u32_f32_sdwa v6, v8 dst_sel:WORD_1 dst_unused:UNUSED_PAD src0_sel:DWORD
	v_cvt_u32_f32_sdwa v7, v9 dst_sel:BYTE_3 dst_unused:UNUSED_PAD src0_sel:DWORD
	v_max_f32_e32 v4, 1.0, v4
	v_max_f32_e32 v5, 1.0, v5
	v_cvt_u32_f32_e32 v8, v2
	v_cvt_u32_f32_e32 v3, v3
	v_cvt_u32_f32_sdwa v4, v4 dst_sel:WORD_1 dst_unused:UNUSED_PAD src0_sel:DWORD
	v_cvt_u32_f32_sdwa v5, v5 dst_sel:BYTE_3 dst_unused:UNUSED_PAD src0_sel:DWORD
	v_lshl_or_b32 v0, v10, 8, v0
	v_or3_b32 v2, v0, v6, v7
	v_lshl_or_b32 v0, v3, 8, v8
	v_or3_b32 v3, v0, v4, v5
	global_store_dwordx2 v[70:71], v[66:67], off nt
	global_store_dwordx2 v[52:53], v[48:49], off nt
	global_store_dwordx2 v[36:37], v[32:33], off nt
	global_store_dwordx2 v[18:19], v[14:15], off nt
	global_store_dwordx2 v[18:19], v[2:3], off offset:32 nt

; #define WAIT_BAR(N) asm volatile("s_waitcnt vmcnt(" #N ") lgkmcnt(0)\n\ts_barrier":::"memory")
;   #define DMA_K(t,slot) glds16(ksrc+(long)(t)*KVBLK*DM,(unsigned)__builtin_amdgcn_readfirstlane(kdst+(slot)))
; template<int MODE,int THRL> __device__ __forceinline__ void attn_unit(int b,int h,int qb,const bf16*Q,const bf16*__restrict__ K,const bf16*__restrict__ V,bf16*O,char*shm,const float*aux0,const float*aux1,const float*aux2){
;     ...
;   const bf16*Kh=K+(rowbase+(long)T0*KVBLK)*DM+h*D,*Vh=V+(rowbase+(long)T0*KVBLK)*DM+h*D;
;   const unsigned lds0=(unsigned)(uintptr_t)shm;
;   float*wsf=(float*)(shm+LDS_WS)+wid*64;
;   const bf16*ksrc=Kh+(long)lane*DM+wid*8;
;   const bf16*vsrc=Vh+(long)(16*(wid&3)+(lane>>2))*DM+(wid>>2)*32+(lane&3)*8;
;   const unsigned kdst=lds0+LDS_K+wid*1024, vdst=lds0+LDS_V+wid*1024;
;     ...
;   const int vb0=(int)(lds0+LDS_V)+((lane>>4)&1)*32+(lane&3)*8+(4*hi+((lane&15)>>2))*64;
;   const char*Kbase=shm+LDS_K; bf16x8 kf[8];
;   const lds_cptr shm3=(lds_cptr)shm; const lds_cptr kp0=shm3+LDS_K+hi*1024+r32*16; const lds_cptr vp0=shm3+LDS_V+((lane>>4)&1)*32+(lane&3)*8+(4*hi+((lane&15)>>2))*64;
;   const int NT=(q0+QB)/KVBLK-T0;
;   const lds_fptr tab=(lds_fptr)(shm3+TAB_OFF);
;   const int dbase=4*qb+(wid>>1)-T0, ibase=32*(wid&1)+r32+128; const lds_fptr tabh=(MODE==0)?tab+64*T0:tab;
;   if(MODE==0){
;     const lds_fptr bp=tab+8192;
;     const int nkeys=q0+QB; const float*cum=aux0+(long)(b*NHEAD+h)*SEQ;
;     for(int j0=64*T0+tid;j0<nkeys;j0+=2048){ float cv[4];
;       #pragma unroll
;       for(int u4=0;u4<4;++u4){const int jj=j0+512*u4; cv[u4]=(jj<nkeys)?cum[jj]:0.f;}
;       #pragma unroll
;       for(int u4=0;u4<4;++u4){const int jj=j0+512*u4; if(jj<nkeys) tab[jj]=-(cv[u4]+bp[jj>>6])*LOG2E;} }
;   } else {
;     if(tid<257) tab[tid]=aux0[tid]*LOG2E;
;   }
;   DMA_K(0,0);DMA_V(0,0);DMA_K(1,SLOTB);
;   bf16x8 qr[4];
;   #pragma unroll
;   for(int d0=0;d0<4;++d0)qr[d0]=*reinterpret_cast<const bf16x8*>(&Qw[(long)r32*DM+d0*16+hi*8]);
;   float mhat=0.f,l_reg=0.f;f32x16 o[2];o[0]=f32x16{};o[1]=f32x16{};f32x16 negm=f32x16{};asm volatile("":"+v"(negm));
;   const int qrel=wid*QBLK+r32;
;     ...
;   bool resc=false;
;     ...
;   f32x16 pA0,pA1,pB0,pB1;
;   int sl_prev=0,sl_cur=0,sl_next=SLOTB;
;     ...
;   DMA_K(2,2*SLOTB);
;   WAIT_BAR(3);
;   qkt(pA0,pA1,Kbase,qr,negm,r32,hi);asm volatile("s_nop 15\n\ts_nop 7":"+v"(pA0),"+v"(pA1));CMASK(pA0,pA1,0);
.LBB0_747:
	s_or_b64 exec, exec, s[10:11]
	s_lshl_b32 s4, s1, 6
	s_xor_b64 s[48:49], s[8:9], -1
	s_ashr_i32 s58, s44, 6
	s_ashr_i32 s5, s4, 31
	s_add_u32 s6, s90, s68
	s_addc_u32 s7, s91, 0
	s_lshl_b64 s[6:7], s[6:7], 10
	v_readlane_b32 s1, v255, 37
	s_add_u32 s1, s1, s6
	s_addc_u32 s9, s43, s7
	s_lshl_b64 s[4:5], s[4:5], 1
	s_add_u32 s8, s1, s4
	s_addc_u32 s9, s9, s5
	s_add_u32 s1, s59, s6
	s_addc_u32 s7, s89, s7
	s_add_u32 s6, s1, s4
	v_lshlrev_b32_e32 v0, 10, v217
	s_addc_u32 s7, s7, s5
	v_lshl_add_u64 v[2:3], s[8:9], 0, v[0:1]
	s_lshl_b32 s1, s58, 4
	v_lshrrev_b32_e32 v0, 2, v217
	s_lshl_b32 s8, s58, 3
	v_and_or_b32 v0, s1, 48, v0
	s_ashr_i32 s9, s8, 31
	v_lshlrev_b32_e32 v0, 10, v0
	s_ashr_i32 s1, s44, 3
	v_lshl_add_u64 v[204:205], s[8:9], 1, v[2:3]
	v_lshl_add_u64 v[2:3], s[6:7], 0, v[0:1]
	s_and_b32 s6, s1, 0xffffffe0
	s_ashr_i32 s7, s6, 31
	s_lshl_b32 s1, s58, 10
	s_cmp_lg_u32 0, -1
	v_lshl_add_u64 v[2:3], s[6:7], 1, v[2:3]
	s_cselect_b32 s6, 0, 0
	s_add_i32 s62, s1, s6
	s_lshr_b32 s6, s16, 6
	s_sub_i32 s40, s6, s57
	s_lshl_b32 s6, s68, 2
	s_add_i32 s71, s6, 0
	s_lshl_b32 s6, s58, 5
	s_mov_b64 s[2:3], s[96:97]
	s_add_i32 s97, s62, 0x6000
	s_add_i32 s71, s71, 0x15000
	s_or_b64 s[8:9], s[90:91], s[94:95]
	s_ashr_i32 s7, s6, 31
	s_add_u32 s8, s8, s6
	s_addc_u32 s9, s9, s7
	s_lshl_b64 s[8:9], s[8:9], 10
	v_readlane_b32 s7, v255, 36
	v_lshlrev_b32_e32 v222, 3, v52
	s_add_u32 s7, s7, s8
	v_and_b32_e32 v254, 24, v222
	s_addc_u32 s8, s0, s9
	v_and_b32_e32 v223, 31, v52
	v_lshrrev_b32_e32 v253, 5, v217
	v_lshlrev_b32_e32 v0, 1, v254
	s_add_u32 s92, s7, s4
	s_mov_b32 s4, m0
	s_mov_b32 m0, s62
	s_nop 0
	global_load_lds_dwordx4 v[204:205], off
	s_mov_b32 m0, s4
	v_lshl_add_u64 v[206:207], v[2:3], 0, v[0:1]
	v_lshlrev_b32_e32 v0, 10, v253
	v_lshlrev_b32_e32 v2, 4, v223
	s_mov_b32 s4, m0
	s_mov_b32 m0, s97
	s_nop 0
	global_load_lds_dwordx4 v[206:207], off
	s_mov_b32 m0, s4
	v_lshlrev_b32_e32 v244, 4, v253
	v_add3_u32 v247, 0, v0, v2
	s_addc_u32 s93, s8, s5
	v_lshl_add_u64 v[2:3], v[204:205], 0, s[50:51]
	s_add_i32 s4, s62, 0x2000
	s_mov_b32 s5, m0
	s_mov_b32 m0, s4
	s_nop 0
	global_load_lds_dwordx4 v[2:3], off
	s_mov_b32 m0, s5
	v_lshl_or_b32 v0, v223, 10, v244
	global_load_dwordx4 v[140:143], v0, s[92:93] nt
	global_load_dwordx4 v[136:139], v0, s[92:93] offset:32 nt
	global_load_dwordx4 v[132:135], v0, s[92:93] offset:64 nt
	global_load_dwordx4 v[128:131], v0, s[92:93] offset:96 nt
	v_mov_b32_e32 v2, v1
	v_mov_b32_e32 v3, v1
	v_mov_b32_e32 v4, v1
	v_mov_b32_e32 v5, v1
	v_mov_b32_e32 v6, v1
	v_mov_b32_e32 v7, v1
	v_mov_b32_e32 v8, v1
	v_mov_b32_e32 v9, v1
	v_mov_b32_e32 v10, v1
	v_mov_b32_e32 v11, v1
	v_mov_b32_e32 v12, v1
	v_mov_b32_e32 v13, v1
	v_mov_b32_e32 v14, v1
	v_mov_b32_e32 v15, v1
	v_mov_b32_e32 v0, v1
	v_mov_b64_e32 v[16:17], v[14:15]
	v_mov_b64_e32 v[14:15], v[12:13]
	v_mov_b64_e32 v[12:13], v[10:11]
	v_mov_b64_e32 v[10:11], v[8:9]
	v_mov_b64_e32 v[8:9], v[6:7]
	v_mov_b64_e32 v[6:7], v[4:5]
	v_mov_b64_e32 v[4:5], v[2:3]
	v_mov_b64_e32 v[2:3], v[0:1]
	v_lshl_add_u64 v[18:19], v[204:205], 0, s[74:75]
	s_add_i32 s4, s62, 0x4000
	s_mov_b32 s5, m0
	s_mov_b32 m0, s4
	s_nop 0
	global_load_lds_dwordx4 v[18:19], off
	s_mov_b32 m0, s5
	s_waitcnt vmcnt(3) lgkmcnt(0)
	s_barrier
	ds_read_b128 v[34:37], v247 offset:512
	ds_read_b128 v[38:41], v247
	v_add_u32_e32 v0, s71, v244
	s_mov_b64 s[4:5], -1
	s_cmp_lt_i32 s40, 5
	s_waitcnt vmcnt(3) lgkmcnt(0)
	v_mfma_f32_32x32x16_bf16 v[18:33], v[38:41], v[140:143], v[2:17]
	v_mfma_f32_32x32x16_bf16 v[2:17], v[34:37], v[140:143], v[2:17]
	ds_read_b128 v[34:37], v247 offset:2560
	ds_read_b128 v[38:41], v247 offset:2048
	s_waitcnt vmcnt(2) lgkmcnt(0)
	v_mfma_f32_32x32x16_bf16 v[18:33], v[38:41], v[136:139], v[18:33]
	v_mfma_f32_32x32x16_bf16 v[2:17], v[34:37], v[136:139], v[2:17]
	ds_read_b128 v[34:37], v247 offset:4608
	ds_read_b128 v[38:41], v247 offset:4096
	s_waitcnt vmcnt(1) lgkmcnt(0)
	v_mfma_f32_32x32x16_bf16 v[18:33], v[38:41], v[132:135], v[18:33]
	v_mfma_f32_32x32x16_bf16 v[2:17], v[34:37], v[132:135], v[2:17]
	ds_read_b128 v[34:37], v247 offset:6656
	ds_read_b128 v[38:41], v247 offset:6144
	s_waitcnt vmcnt(0) lgkmcnt(0)
	v_mfma_f32_32x32x16_bf16 v[18:33], v[38:41], v[128:131], v[18:33]
	v_mfma_f32_32x32x16_bf16 v[2:17], v[34:37], v[128:131], v[2:17]
	s_nop 15
	s_nop 7
	ds_read_b128 v[38:41], v0
	ds_read_b128 v[42:45], v0 offset:32
	ds_read_b128 v[34:37], v0 offset:128
	s_waitcnt lgkmcnt(2)
	s_nop 6
	v_pk_add_f32 v[50:51], v[38:39], v[18:19]
	v_pk_add_f32 v[48:49], v[40:41], v[20:21]
	ds_read_b128 v[18:21], v0 offset:160
	s_waitcnt lgkmcnt(2)
	v_pk_add_f32 v[46:47], v[22:23], v[42:43]
	v_pk_add_f32 v[44:45], v[24:25], v[44:45]
	ds_read_b128 v[38:41], v0 offset:64
	ds_read_b128 v[22:25], v0 offset:192
	s_waitcnt lgkmcnt(1)
	v_pk_add_f32 v[42:43], v[26:27], v[38:39]
	v_pk_add_f32 v[40:41], v[28:29], v[40:41]
	ds_read_b128 v[54:57], v0 offset:96
	ds_read_b128 v[26:29], v0 offset:224
	v_lshlrev_b32_e32 v0, 2, v253
	s_waitcnt lgkmcnt(1)
	v_pk_add_f32 v[38:39], v[30:31], v[54:55]
	v_pk_add_f32 v[30:31], v[32:33], v[56:57]
	s_cbranch_scc1 .LBB0_749
	v_lshlrev_b32_e32 v242, 2, v253
	s_mov_b64 s[4:5], 0

; template<int MODE> __device__ __forceinline__ void hook(f32x16&p0,f32x16&p1,int t,int NT,int qrel,int hi,lds_fptr tab,int dbase,int ibase){
;     ...
;     const int delta=dbase-t;
;     if(delta<0||delta>8){
;       #pragma unroll
; template<int MODE,int THRL> __device__ __forceinline__ void attn_unit(int b,int h,int qb,const bf16*Q,const bf16*__restrict__ K,const bf16*__restrict__ V,bf16*O,char*shm,const float*aux0,const float*aux1,const float*aux2){
;     ...
;   const bf16*Kh=K+(rowbase+(long)T0*KVBLK)*DM+h*D,*Vh=V+(rowbase+(long)T0*KVBLK)*DM+h*D;
;   const unsigned lds0=(unsigned)(uintptr_t)shm;
;   float*wsf=(float*)(shm+LDS_WS)+wid*64;
;   const bf16*ksrc=Kh+(long)lane*DM+wid*8;
;   const bf16*vsrc=Vh+(long)(16*(wid&3)+(lane>>2))*DM+(wid>>2)*32+(lane&3)*8;
;   const unsigned kdst=lds0+LDS_K+wid*1024, vdst=lds0+LDS_V+wid*1024;
;     ...
;   const int vb0=(int)(lds0+LDS_V)+((lane>>4)&1)*32+(lane&3)*8+(4*hi+((lane&15)>>2))*64;
;   const char*Kbase=shm+LDS_K; bf16x8 kf[8];
;   const lds_cptr shm3=(lds_cptr)shm; const lds_cptr kp0=shm3+LDS_K+hi*1024+r32*16; const lds_cptr vp0=shm3+LDS_V+((lane>>4)&1)*32+(lane&3)*8+(4*hi+((lane&15)>>2))*64;
;   const int NT=(q0+QB)/KVBLK-T0;
;   const lds_fptr tab=(lds_fptr)(shm3+TAB_OFF);
;   const int dbase=4*qb+(wid>>1)-T0, ibase=32*(wid&1)+r32+128; const lds_fptr tabh=(MODE==0)?tab+64*T0:tab;
;   if(MODE==0){
;     const lds_fptr bp=tab+8192;
;     const int nkeys=q0+QB; const float*cum=aux0+(long)(b*NHEAD+h)*SEQ;
;     for(int j0=64*T0+tid;j0<nkeys;j0+=2048){ float cv[4];
;       #pragma unroll
;       for(int u4=0;u4<4;++u4){const int jj=j0+512*u4; cv[u4]=(jj<nkeys)?cum[jj]:0.f;}
;       #pragma unroll
;       for(int u4=0;u4<4;++u4){const int jj=j0+512*u4; if(jj<nkeys) tab[jj]=-(cv[u4]+bp[jj>>6])*LOG2E;} }
;   } else {
;     if(tid<257) tab[tid]=aux0[tid]*LOG2E;
;   }
;   DMA_K(0,0);DMA_V(0,0);DMA_K(1,SLOTB);
;   bf16x8 qr[4];
;   #pragma unroll
;   for(int d0=0;d0<4;++d0)qr[d0]=*reinterpret_cast<const bf16x8*>(&Qw[(long)r32*DM+d0*16+hi*8]);
;   float mhat=0.f,l_reg=0.f;f32x16 o[2];o[0]=f32x16{};o[1]=f32x16{};f32x16 negm=f32x16{};asm volatile("":"+v"(negm));
;   const int qrel=wid*QBLK+r32;
;     ...
;   bool resc=false;
;     ...
;   f32x16 pA0,pA1,pB0,pB1;
;   int sl_prev=0,sl_cur=0,sl_next=SLOTB;
;     ...
;   DMA_K(2,2*SLOTB);
;   WAIT_BAR(3);
;   qkt(pA0,pA1,Kbase,qr,negm,r32,hi);asm volatile("s_nop 15\n\ts_nop 7":"+v"(pA0),"+v"(pA1));CMASK(pA0,pA1,0);
.LBB0_845:
	s_or_b64 exec, exec, s[4:5]
	s_and_b64 s[4:5], s[6:7], exec
	s_cselect_b32 s1, s76, s83
	s_ashr_i32 s34, s14, 6
	s_lshl_b32 s17, s1, 8
	s_lshl_b32 s15, s34, 5
	s_or_b32 s4, s90, s17
	s_ashr_i32 s5, s15, 31
	s_add_u32 s4, s4, s15
	s_addc_u32 s5, s91, s5
	s_lshl_b64 s[4:5], s[4:5], 10
	s_add_u32 s12, s26, s4
	s_addc_u32 s13, s27, s5
	s_lshl_b32 s22, s1, 2
	s_add_i32 s4, s22, -8
	s_cmp_gt_u32 s1, 2
	s_cselect_b32 s94, s4, 0
	s_lshl_b64 s[4:5], s[94:95], 15
	s_add_u32 s4, s4, s8
	s_addc_u32 s5, s5, s9
	s_lshl_b64 s[4:5], s[4:5], 1
	s_add_u32 s18, s28, s4
	v_and_b32_e32 v217, 63, v34
	s_addc_u32 s19, s29, s5
	s_add_u32 s4, s30, s4
	v_lshlrev_b32_e32 v0, 10, v217
	s_addc_u32 s5, s31, s5
	v_lshl_add_u64 v[2:3], s[18:19], 0, v[0:1]
	s_lshl_b32 s1, s34, 4
	v_bfe_u32 v0, v34, 2, 4
	s_lshl_b32 s18, s34, 3
	v_and_or_b32 v0, s1, 48, v0
	s_ashr_i32 s19, s18, 31
	v_lshlrev_b32_e32 v0, 10, v0
	s_ashr_i32 s1, s14, 3
	v_lshl_add_u64 v[220:221], s[18:19], 1, v[2:3]
	v_lshl_add_u64 v[2:3], s[4:5], 0, v[0:1]
	s_and_b32 s4, s1, 0xffffffe0
	s_ashr_i32 s5, s4, 31
	s_lshl_b32 s1, s34, 10
	v_lshlrev_b32_e32 v241, 3, v34
	s_cmp_lg_u32 0, -1
	v_lshl_add_u64 v[2:3], s[4:5], 1, v[2:3]
	v_and_b32_e32 v244, 24, v241
	s_cselect_b32 s4, 0, 0
	v_and_b32_e32 v242, 31, v34
	v_lshlrev_b32_e32 v0, 1, v244
	s_add_i32 s37, s1, s4
	s_mov_b32 s4, m0
	s_mov_b32 m0, s37
	s_nop 0
	global_load_lds_dwordx4 v[220:221], off
	s_mov_b32 m0, s4
	v_bfe_u32 v243, v34, 5, 1
	v_lshl_add_u64 v[222:223], v[2:3], 0, v[0:1]
	s_add_i32 s38, s37, 0x6000
	s_mov_b32 s4, m0
	s_mov_b32 m0, s38
	s_nop 0
	global_load_lds_dwordx4 v[222:223], off
	s_mov_b32 m0, s4
	v_lshlrev_b32_e32 v0, 10, v242
	v_lshl_add_u64 v[2:3], v[220:221], 0, s[50:51]
	s_add_i32 s4, s37, 0x2000
	s_mov_b32 s5, m0
	s_mov_b32 m0, s4
	s_nop 0
	global_load_lds_dwordx4 v[2:3], off
	s_mov_b32 m0, s5
	v_lshl_or_b32 v0, v243, 4, v0
	global_load_dwordx4 v[148:151], v0, s[12:13] nt
	global_load_dwordx4 v[136:139], v0, s[12:13] offset:32 nt
	global_load_dwordx4 v[132:135], v0, s[12:13] offset:64 nt
	global_load_dwordx4 v[128:131], v0, s[12:13] offset:96 nt
	v_mov_b32_e32 v2, v1
	v_mov_b32_e32 v3, v1
	v_mov_b32_e32 v4, v1
	v_mov_b32_e32 v5, v1
	v_mov_b32_e32 v6, v1
	v_mov_b32_e32 v7, v1
	v_mov_b32_e32 v8, v1
	v_mov_b32_e32 v9, v1
	v_mov_b32_e32 v10, v1
	v_mov_b32_e32 v11, v1
	v_mov_b32_e32 v12, v1
	v_mov_b32_e32 v13, v1
	v_mov_b32_e32 v14, v1
	v_mov_b32_e32 v15, v1
	v_lshlrev_b32_e32 v0, 10, v243
	v_lshlrev_b32_e32 v16, 4, v242
	v_add3_u32 v250, 0, v0, v16
	v_mov_b32_e32 v0, v1
	v_mov_b64_e32 v[16:17], v[14:15]
	v_mov_b64_e32 v[14:15], v[12:13]
	v_mov_b64_e32 v[12:13], v[10:11]
	v_mov_b64_e32 v[10:11], v[8:9]
	v_mov_b64_e32 v[8:9], v[6:7]
	v_mov_b64_e32 v[6:7], v[4:5]
	v_mov_b64_e32 v[4:5], v[2:3]
	v_mov_b64_e32 v[2:3], v[0:1]
	v_lshl_add_u64 v[18:19], v[220:221], 0, s[74:75]
	s_add_i32 s4, s37, 0x4000
	s_mov_b32 s5, m0
	s_mov_b32 m0, s4
	s_nop 0
	global_load_lds_dwordx4 v[18:19], off
	s_mov_b32 m0, s5
	s_waitcnt vmcnt(3) lgkmcnt(0)
	s_barrier
	ds_read_b128 v[36:39], v250
	ds_read_b128 v[40:43], v250 offset:512
	s_ashr_i32 s23, s14, 7
	s_sub_i32 s4, s22, s94
	s_and_b32 s24, s15, 32
	s_add_i32 s36, s23, s4
	v_or_b32_e32 v0, s24, v242
	v_or_b32_e32 v248, 0x80, v0
	s_cmp_lt_u32 s36, 9
	s_mov_b64 s[4:5], -1
	s_waitcnt vmcnt(3) lgkmcnt(1)
	v_mfma_f32_32x32x16_bf16 v[18:33], v[36:39], v[148:151], v[2:17]
	s_waitcnt lgkmcnt(0)
	v_mfma_f32_32x32x16_bf16 v[2:17], v[40:43], v[148:151], v[2:17]
	ds_read_b128 v[36:39], v250 offset:2048
	ds_read_b128 v[40:43], v250 offset:2560
	s_waitcnt vmcnt(2) lgkmcnt(1)
	v_mfma_f32_32x32x16_bf16 v[18:33], v[36:39], v[136:139], v[18:33]
	s_waitcnt lgkmcnt(0)
	v_mfma_f32_32x32x16_bf16 v[2:17], v[40:43], v[136:139], v[2:17]
	ds_read_b128 v[36:39], v250 offset:4096
	ds_read_b128 v[40:43], v250 offset:4608
	s_waitcnt vmcnt(1) lgkmcnt(1)
	v_mfma_f32_32x32x16_bf16 v[18:33], v[36:39], v[132:135], v[18:33]
	s_waitcnt lgkmcnt(0)
	v_mfma_f32_32x32x16_bf16 v[2:17], v[40:43], v[132:135], v[2:17]
	ds_read_b128 v[36:39], v250 offset:6144
	ds_read_b128 v[40:43], v250 offset:6656
	s_waitcnt vmcnt(0) lgkmcnt(1)
	v_mfma_f32_32x32x16_bf16 v[18:33], v[36:39], v[128:131], v[18:33]
	s_waitcnt lgkmcnt(0)
	v_mfma_f32_32x32x16_bf16 v[2:17], v[40:43], v[128:131], v[2:17]
	s_nop 15
	s_nop 7
	s_cbranch_scc0 .LBB0_851
	s_cmp_lt_u32 s36, 3
	s_cbranch_scc0 .LBB0_848
; template<int MODE> __device__ __forceinline__ void hook(f32x16&p0,f32x16&p1,int t,int NT,int qrel,int hi,lds_fptr tab,int dbase,int ibase){
;     ...
;     } else { const int ib=64*delta+ibase-4*hi;
;       #pragma unroll
;       for(int r=0;r<16;++r){ const int kc=(r&3)+8*(r>>2); int i0=ib-kc, i1=ib-32-kc; i0=i0>256?256:i0; i1=i1>256?256:i1; p0[r]+=tab[i0]; p1[r]+=tab[i1]; }
	v_lshlrev_b32_e32 v0, 2, v243
	v_sub_u32_e32 v0, v248, v0
	v_lshl_add_u32 v0, s36, 6, v0
	v_min_u32_e32 v36, 0x120, v0
	s_add_i32 s4, 0, 0x15000
	v_min_u32_e32 v37, 0x101, v0
	v_min_u32_e32 v38, 0x121, v0
	v_min_u32_e32 v39, 0x102, v0
	v_min_u32_e32 v40, 0x122, v0
	v_min_u32_e32 v41, 0x103, v0
	v_min_u32_e32 v35, 0x100, v0
	v_lshl_add_u32 v36, v36, 2, s4
	v_lshlrev_b32_e32 v37, 2, v37
	v_lshl_add_u32 v38, v38, 2, s4
	v_lshlrev_b32_e32 v39, 2, v39
	v_lshl_add_u32 v40, v40, 2, s4
	v_min_u32_e32 v42, 0x123, v0
	v_lshlrev_b32_e32 v41, 2, v41
	v_lshl_add_u32 v35, v35, 2, s4
	v_add_u32_e32 v36, 0xffffff80, v36
	v_add3_u32 v37, s4, v37, -4
	v_add_u32_e32 v38, 0xffffff7c, v38
	v_add3_u32 v39, s4, v39, -8
	v_add_u32_e32 v40, 0xffffff78, v40
	v_add3_u32 v41, s4, v41, -12
	v_lshl_add_u32 v42, v42, 2, s4
	v_add_u32_e32 v42, 0xffffff74, v42
	ds_read_b32 v64, v35
	ds_read_b32 v36, v36
	ds_read_b32 v65, v37
	ds_read_b32 v37, v38
	ds_read_b32 v62, v39
	ds_read_b32 v38, v40
	ds_read_b32 v63, v41
	ds_read_b32 v39, v42
	v_min_u32_e32 v35, 0x108, v0
	v_min_u32_e32 v40, 0x128, v0
	v_min_u32_e32 v41, 0x109, v0
	v_min_u32_e32 v46, 0x12b, v0
	v_lshl_add_u32 v35, v35, 2, s4
	v_lshl_add_u32 v40, v40, 2, s4
	v_min_u32_e32 v42, 0x129, v0
	v_lshl_add_u32 v41, v41, 2, s4
	v_min_u32_e32 v43, 0x10a, v0
	v_min_u32_e32 v44, 0x12a, v0
	v_min_u32_e32 v45, 0x10b, v0
	v_lshl_add_u32 v46, v46, 2, s4
	v_subrev_u32_e32 v35, 32, v35
	v_add_u32_e32 v40, 0xffffff60, v40
	v_subrev_u32_e32 v41, 36, v41
	v_lshl_add_u32 v42, v42, 2, s4
	v_lshl_add_u32 v43, v43, 2, s4
	v_lshl_add_u32 v44, v44, 2, s4
	v_lshl_add_u32 v45, v45, 2, s4
	v_add_u32_e32 v47, 0xffffff54, v46
	v_add_u32_e32 v42, 0xffffff5c, v42
	v_subrev_u32_e32 v43, 40, v43
	v_add_u32_e32 v44, 0xffffff58, v44
	v_subrev_u32_e32 v45, 44, v45
	ds_read_b32 v60, v35
	ds_read_b32 v40, v40
	ds_read_b32 v61, v41
	ds_read_b32 v41, v42
	ds_read_b32 v58, v43
	ds_read_b32 v46, v44
	ds_read_b32 v59, v45
	ds_read_b32 v47, v47
	v_min_u32_e32 v48, 0x132, v0
	v_lshl_add_u32 v48, v48, 2, s4
	v_min_u32_e32 v35, 0x110, v0
	v_min_u32_e32 v42, 0x130, v0
	v_min_u32_e32 v43, 0x111, v0
	v_add_u32_e32 v50, 0xffffff38, v48
	v_min_u32_e32 v48, 0x113, v0
	v_lshl_add_u32 v35, v35, 2, s4
	v_lshl_add_u32 v42, v42, 2, s4
	v_min_u32_e32 v44, 0x131, v0
	v_lshl_add_u32 v43, v43, 2, s4
	v_min_u32_e32 v45, 0x112, v0
	v_min_u32_e32 v49, 0x133, v0
	v_lshl_add_u32 v48, v48, 2, s4
	v_subrev_u32_e32 v35, 64, v35
	v_add_u32_e32 v42, 0xffffff40, v42
	v_add_u32_e32 v43, 0xffffffbc, v43
	v_lshl_add_u32 v44, v44, 2, s4
	v_lshl_add_u32 v45, v45, 2, s4
	v_add_u32_e32 v51, 0xffffffb4, v48
	v_lshl_add_u32 v48, v49, 2, s4
	v_add_u32_e32 v44, 0xffffff3c, v44
	v_add_u32_e32 v45, 0xffffffb8, v45
	v_add_u32_e32 v52, 0xffffff34, v48
	ds_read_b32 v56, v35
	ds_read_b32 v48, v42
	ds_read_b32 v57, v43
	ds_read_b32 v49, v44
	ds_read_b32 v54, v45
	ds_read_b32 v50, v50
	ds_read_b32 v55, v51
	ds_read_b32 v51, v52
	s_waitcnt lgkmcnt(12)
	v_pk_add_f32 v[42:43], v[6:7], v[40:41]
	s_waitcnt lgkmcnt(8)
	v_pk_add_f32 v[40:41], v[8:9], v[46:47]
	v_min_u32_e32 v47, 0x119, v0
	v_pk_add_f32 v[44:45], v[4:5], v[38:39]
	s_waitcnt lgkmcnt(4)
	v_pk_add_f32 v[38:39], v[10:11], v[48:49]
	v_min_u32_e32 v48, 0x139, v0
	v_lshl_add_u32 v47, v47, 2, s4
	v_add_u32_e32 v49, 0xffffff9c, v47
	v_lshl_add_u32 v47, v48, 2, s4
	v_min_u32_e32 v48, 0x11a, v0
	v_min_u32_e32 v52, 0x13a, v0
	v_lshl_add_u32 v48, v48, 2, s4
	v_add_u32_e32 v53, 0xffffff98, v48
	v_lshl_add_u32 v48, v52, 2, s4
	v_min_u32_e32 v35, 0x118, v0
	v_min_u32_e32 v46, 0x138, v0
	v_add_u32_e32 v52, 0xffffff18, v48
	v_min_u32_e32 v48, 0x11b, v0
	v_lshl_add_u32 v35, v35, 2, s4
	v_lshl_add_u32 v46, v46, 2, s4
	v_min_u32_e32 v0, 0x13b, v0
	v_lshl_add_u32 v48, v48, 2, s4
	v_add_u32_e32 v35, 0xffffffa0, v35
	v_add_u32_e32 v46, 0xffffff20, v46
	v_add_u32_e32 v47, 0xffffff1c, v47
	v_add_u32_e32 v67, 0xffffff94, v48
	v_lshl_add_u32 v0, v0, 2, s4
	v_add_u32_e32 v0, 0xffffff14, v0
	ds_read_b32 v48, v35
	ds_read_b32 v46, v46
	ds_read_b32 v47, v47
	ds_read_b32 v66, v53
	ds_read_b32 v35, v52
	ds_read_b32 v67, v67
	ds_read_b32 v68, v0
	ds_read_b32 v49, v49
	v_pk_add_f32 v[36:37], v[2:3], v[36:37]
	s_waitcnt lgkmcnt(8)
	v_pk_add_f32 v[52:53], v[12:13], v[50:51]
	s_waitcnt lgkmcnt(5)
	v_pk_add_f32 v[50:51], v[14:15], v[46:47]
	s_waitcnt lgkmcnt(3)
	v_add_f32_e32 v0, v16, v35
	s_waitcnt lgkmcnt(2)
	v_pk_add_f32 v[46:47], v[32:33], v[66:67]
	s_waitcnt lgkmcnt(0)
	v_pk_add_f32 v[48:49], v[30:31], v[48:49]
	v_pk_add_f32 v[54:55], v[28:29], v[54:55]
	v_pk_add_f32 v[56:57], v[26:27], v[56:57]
	v_pk_add_f32 v[58:59], v[24:25], v[58:59]
	v_pk_add_f32 v[60:61], v[22:23], v[60:61]
	v_pk_add_f32 v[62:63], v[20:21], v[62:63]
	v_pk_add_f32 v[64:65], v[18:19], v[64:65]
	v_add_f32_e32 v35, v17, v68
	s_mov_b64 s[4:5], 0

; __device__ __forceinline__ u32x4 pack8(f32x4 v0, f32x4 v1) { u32x4 w; w.x = cvt_pk_bf16(v0[0], v0[1]); w.y = cvt_pk_bf16(v0[2], v0[3]); w.z = cvt_pk_bf16(v1[0], v1[1]); w.w = cvt_pk_bf16(v1[2], v1[3]); return w; }
; __device__ __forceinline__ f32x4 dq4u8(unsigned w) { return (f32x4){(float)(w & 0xffu), (float)((w >> 8) & 0xffu), (float)((w >> 16) & 0xffu), (float)(w >> 24)}; }
;     __device__ __forceinline__ void operator()(f32x4 (&acc)[2][2][4][2], const Unit& u, int wr, int wc, int fr, int fq) const {
;     ...
;             for (int q = 0; q < 2; ++q) { const int m = 2 * mp2 + q; const size_t row = (size_t)(row0 + ai * HALF + m * 16); const unsigned char* gp = (const unsigned char*)G + row * 3072 + col0;
; #pragma unroll
;                 for (int bj = 0; bj < 2; ++bj) { ga[q][bj] = *(const u32x2q*)(gp + n * 1024 + bj * HALF); gb[q][bj] = *(const u32x2q*)(gp + nn * 1024 + bj * HALF); } }
;             asm volatile("" : "+v"(ga[0][0]), "+v"(ga[0][1]), "+v"(ga[1][0]), "+v"(ga[1][1]), "+v"(gb[0][0]), "+v"(gb[0][1]), "+v"(gb[1][0]), "+v"(gb[1][1]));
; #pragma unroll
;             for (int q = 0; q < 2; ++q) { const int m = 2 * mp2 + q; const size_t row = (size_t)(row0 + ai * HALF + m * 16);
;                 if (n < 2) {
; #pragma unroll
;                     for (int bj = 0; bj < 2; ++bj) { const f32x4 d0 = dq4u8(gb[q][bj].x), d1 = dq4u8(gb[q][bj].y);
;                         const f32x4 r0 = dq4u8(ga[q][bj].x) * (f32x4){__builtin_amdgcn_rcpf(d0[0]), __builtin_amdgcn_rcpf(d0[1]), __builtin_amdgcn_rcpf(d0[2]), __builtin_amdgcn_rcpf(d0[3])};
;                         const f32x4 r1 = dq4u8(ga[q][bj].y) * (f32x4){__builtin_amdgcn_rcpf(d1[0]), __builtin_amdgcn_rcpf(d1[1]), __builtin_amdgcn_rcpf(d1[2]), __builtin_amdgcn_rcpf(d1[3])};
;                         acc[ai][bj][m][0] *= r0; acc[ai][bj][m][1] *= r1; }
;                 } else { bf16_t* mp = MG + row * 1024 + col0;
; #pragma unroll
;                     for (int bj = 0; bj < 2; ++bj) *(u32x4*)(mp + bj * HALF) = pack8(dq4u8(ga[q][bj].x) * (acc[ai][bj][m][0] * (1.0f / 255.0f)), dq4u8(ga[q][bj].y) * (acc[ai][bj][m][1] * (1.0f / 255.0f))); } }
.LBB0_1041:
	s_lshl_b32 s0, s26, 8
	s_ashr_i32 s6, s26, 2
	s_and_b32 s0, s0, 0x300
	s_cmp_gt_i32 s6, 1
	s_cselect_b64 s[28:29], -1, 0
	s_cmp_lt_i32 s6, 2
	v_or_b32_e32 v0, s0, v180
	s_cselect_b64 s[0:1], -1, 0
	s_cmp_lg_u64 s[0:1], 0
	s_addc_u32 s0, s6, 0
	v_lshl_add_u32 v2, s24, 8, v178
	s_lshl_b32 s24, s6, 10
	s_lshl_b32 s26, s0, 10
	v_lshl_add_u64 v[144:145], s[12:13], 0, v[0:1]
	s_ashr_i32 s25, s24, 31
	s_ashr_i32 s27, s26, 31
	v_mad_i64_i32 v[146:147], s[0:1], v2, s56, v[144:145]
	v_lshl_add_u64 v[148:149], v[146:147], 0, s[24:25]
	v_lshl_add_u64 v[146:147], v[146:147], 0, s[26:27]
	v_or_b32_e32 v150, 16, v2
	global_load_dwordx2 v[156:157], v[148:149], off nt
	global_load_dwordx2 v[170:171], v[146:147], off nt
	global_load_dwordx2 v[158:159], v[146:147], off offset:128 nt
	global_load_dwordx2 v[176:177], v[148:149], off offset:128 nt
	v_mad_i64_i32 v[146:147], s[0:1], v150, s56, v[144:145]
	v_lshl_add_u64 v[152:153], v[146:147], 0, s[24:25]
	v_lshl_add_u64 v[146:147], v[146:147], 0, s[26:27]
	global_load_dwordx2 v[154:155], v[152:153], off nt
	global_load_dwordx2 v[148:149], v[146:147], off nt
	s_nop 0
	global_load_dwordx2 v[146:147], v[146:147], off offset:128 nt
	s_nop 0
	global_load_dwordx2 v[152:153], v[152:153], off offset:128 nt
	s_mov_b64 s[6:7], -1
	v_ashrrev_i32_e32 v3, 31, v2
	v_lshlrev_b32_e32 v0, 1, v0
	s_and_b64 vcc, exec, s[28:29]
	s_waitcnt vmcnt(0)
	s_nop 0
	v_cvt_f32_ubyte1_e32 v173, v156
	v_cvt_f32_ubyte0_e32 v172, v156
	v_cvt_f32_ubyte3_e32 v175, v156
	v_cvt_f32_ubyte2_e32 v174, v156
	v_cvt_f32_ubyte1_e32 v169, v157
	v_cvt_f32_ubyte0_e32 v168, v157
	v_cvt_f32_ubyte3_e32 v167, v157
	v_cvt_f32_ubyte2_e32 v166, v157
	v_cvt_f32_ubyte1_e32 v163, v176
	v_cvt_f32_ubyte0_e32 v162, v176
	v_cvt_f32_ubyte3_e32 v165, v176
	v_cvt_f32_ubyte2_e32 v164, v176
	v_cvt_f32_ubyte1_e32 v161, v177
	v_cvt_f32_ubyte0_e32 v160, v177
	v_cvt_f32_ubyte3_e32 v157, v177
	v_cvt_f32_ubyte2_e32 v156, v177
	s_cbranch_vccz .LBB0_1043
	s_mov_b32 s0, 0x3b808081
	v_pk_mul_f32 v[182:183], v[130:131], s[0:1] op_sel_hi:[1,0]
	v_pk_mul_f32 v[184:185], v[128:129], s[0:1] op_sel_hi:[1,0]
	v_lshlrev_b64 v[176:177], 11, v[2:3]
	v_pk_mul_f32 v[186:187], v[182:183], v[174:175]
	v_pk_mul_f32 v[182:183], v[184:185], v[172:173]
	v_pk_mul_f32 v[184:185], v[126:127], s[0:1] op_sel_hi:[1,0]
	v_pk_mul_f32 v[188:189], v[124:125], s[0:1] op_sel_hi:[1,0]
	v_lshl_add_u64 v[176:177], s[10:11], 0, v[176:177]
	v_pk_mul_f32 v[190:191], v[184:185], v[166:167]
	v_pk_mul_f32 v[184:185], v[188:189], v[168:169]
	v_lshl_add_u64 v[176:177], v[176:177], 0, v[0:1]
	v_cvt_pk_bf16_f32 v182, v182, v183
	v_cvt_pk_bf16_f32 v183, v186, v187
	v_cvt_pk_bf16_f32 v184, v184, v185
	v_cvt_pk_bf16_f32 v185, v190, v191
	global_store_dwordx4 v[176:177], v[182:185], off
	v_pk_mul_f32 v[188:189], v[92:93], s[0:1] op_sel_hi:[1,0]
	s_mov_b64 s[6:7], 0
	v_pk_mul_f32 v[182:183], v[98:99], s[0:1] op_sel_hi:[1,0]
	v_pk_mul_f32 v[184:185], v[96:97], s[0:1] op_sel_hi:[1,0]
	v_pk_mul_f32 v[186:187], v[182:183], v[164:165]
	v_pk_mul_f32 v[182:183], v[184:185], v[162:163]
	v_pk_mul_f32 v[184:185], v[94:95], s[0:1] op_sel_hi:[1,0]
	v_cvt_pk_bf16_f32 v182, v182, v183
	v_pk_mul_f32 v[190:191], v[184:185], v[156:157]
	v_pk_mul_f32 v[184:185], v[188:189], v[160:161]
	v_cvt_pk_bf16_f32 v183, v186, v187
	v_cvt_pk_bf16_f32 v184, v184, v185
	v_cvt_pk_bf16_f32 v185, v190, v191
	global_store_dwordx4 v[176:177], v[182:185], off offset:256

; __device__ __forceinline__ u32x4 pack8(f32x4 v0, f32x4 v1) { u32x4 w; w.x = cvt_pk_bf16(v0[0], v0[1]); w.y = cvt_pk_bf16(v0[2], v0[3]); w.z = cvt_pk_bf16(v1[0], v1[1]); w.w = cvt_pk_bf16(v1[2], v1[3]); return w; }
; __device__ __forceinline__ f32x4 dq4u8(unsigned w) { return (f32x4){(float)(w & 0xffu), (float)((w >> 8) & 0xffu), (float)((w >> 16) & 0xffu), (float)(w >> 24)}; }
;     __device__ __forceinline__ void operator()(f32x4 (&acc)[2][2][4][2], const Unit& u, int wr, int wc, int fr, int fq) const {
;     ...
;             for (int q = 0; q < 2; ++q) { const int m = 2 * mp2 + q; const size_t row = (size_t)(row0 + ai * HALF + m * 16); const unsigned char* gp = (const unsigned char*)G + row * 3072 + col0;
; #pragma unroll
;                 for (int bj = 0; bj < 2; ++bj) { ga[q][bj] = *(const u32x2q*)(gp + n * 1024 + bj * HALF); gb[q][bj] = *(const u32x2q*)(gp + nn * 1024 + bj * HALF); } }
;             asm volatile("" : "+v"(ga[0][0]), "+v"(ga[0][1]), "+v"(ga[1][0]), "+v"(ga[1][1]), "+v"(gb[0][0]), "+v"(gb[0][1]), "+v"(gb[1][0]), "+v"(gb[1][1]));
; #pragma unroll
;             for (int q = 0; q < 2; ++q) { const int m = 2 * mp2 + q; const size_t row = (size_t)(row0 + ai * HALF + m * 16);
;                 if (n < 2) {
; #pragma unroll
;                     for (int bj = 0; bj < 2; ++bj) { const f32x4 d0 = dq4u8(gb[q][bj].x), d1 = dq4u8(gb[q][bj].y);
;                         const f32x4 r0 = dq4u8(ga[q][bj].x) * (f32x4){__builtin_amdgcn_rcpf(d0[0]), __builtin_amdgcn_rcpf(d0[1]), __builtin_amdgcn_rcpf(d0[2]), __builtin_amdgcn_rcpf(d0[3])};
;                         const f32x4 r1 = dq4u8(ga[q][bj].y) * (f32x4){__builtin_amdgcn_rcpf(d1[0]), __builtin_amdgcn_rcpf(d1[1]), __builtin_amdgcn_rcpf(d1[2]), __builtin_amdgcn_rcpf(d1[3])};
;                         acc[ai][bj][m][0] *= r0; acc[ai][bj][m][1] *= r1; }
;                 } else { bf16_t* mp = MG + row * 1024 + col0;
; #pragma unroll
;                     for (int bj = 0; bj < 2; ++bj) *(u32x4*)(mp + bj * HALF) = pack8(dq4u8(ga[q][bj].x) * (acc[ai][bj][m][0] * (1.0f / 255.0f)), dq4u8(ga[q][bj].y) * (acc[ai][bj][m][1] * (1.0f / 255.0f))); } }
.LBB0_1049:
	v_or_b32_e32 v176, 32, v2
	v_mad_i64_i32 v[146:147], s[0:1], v176, s56, v[144:145]
	v_lshl_add_u64 v[148:149], v[146:147], 0, s[24:25]
	v_lshl_add_u64 v[146:147], v[146:147], 0, s[26:27]
	v_or_b32_e32 v150, 48, v2
	global_load_dwordx2 v[156:157], v[148:149], off nt
	global_load_dwordx2 v[170:171], v[146:147], off nt
	global_load_dwordx2 v[160:161], v[146:147], off offset:128 nt
	global_load_dwordx2 v[182:183], v[148:149], off offset:128 nt
	v_mad_i64_i32 v[146:147], s[0:1], v150, s56, v[144:145]
	v_lshl_add_u64 v[152:153], v[146:147], 0, s[24:25]
	v_lshl_add_u64 v[146:147], v[146:147], 0, s[26:27]
	global_load_dwordx2 v[154:155], v[152:153], off nt
	global_load_dwordx2 v[148:149], v[146:147], off nt
	s_nop 0
	global_load_dwordx2 v[146:147], v[146:147], off offset:128 nt
	s_nop 0
	global_load_dwordx2 v[152:153], v[152:153], off offset:128 nt
	s_mov_b64 s[28:29], -1
	s_and_b64 vcc, exec, s[6:7]
	s_waitcnt vmcnt(0)
	s_nop 0
	v_cvt_f32_ubyte1_e32 v173, v156
	v_cvt_f32_ubyte0_e32 v172, v156
	v_cvt_f32_ubyte3_e32 v175, v156
	v_cvt_f32_ubyte2_e32 v174, v156
	v_cvt_f32_ubyte1_e32 v169, v157
	v_cvt_f32_ubyte0_e32 v168, v157
	v_cvt_f32_ubyte3_e32 v167, v157
	v_cvt_f32_ubyte2_e32 v166, v157
	v_cvt_f32_ubyte1_e32 v163, v182
	v_cvt_f32_ubyte0_e32 v162, v182
	v_cvt_f32_ubyte3_e32 v165, v182
	v_cvt_f32_ubyte2_e32 v164, v182
	v_cvt_f32_ubyte1_e32 v159, v183
	v_cvt_f32_ubyte0_e32 v158, v183
	v_cvt_f32_ubyte3_e32 v157, v183
	v_cvt_f32_ubyte2_e32 v156, v183
	s_cbranch_vccnz .LBB0_1051
	s_mov_b32 s0, 0x3b808081
	v_ashrrev_i32_e32 v177, 31, v176
	v_pk_mul_f32 v[182:183], v[114:115], s[0:1] op_sel_hi:[1,0]
	v_pk_mul_f32 v[184:185], v[112:113], s[0:1] op_sel_hi:[1,0]
	v_lshlrev_b64 v[176:177], 11, v[176:177]
	v_pk_mul_f32 v[186:187], v[182:183], v[174:175]
	v_pk_mul_f32 v[182:183], v[184:185], v[172:173]
	v_pk_mul_f32 v[184:185], v[110:111], s[0:1] op_sel_hi:[1,0]
	v_pk_mul_f32 v[188:189], v[108:109], s[0:1] op_sel_hi:[1,0]
	v_lshl_add_u64 v[176:177], s[10:11], 0, v[176:177]
	v_pk_mul_f32 v[190:191], v[184:185], v[166:167]
	v_pk_mul_f32 v[184:185], v[188:189], v[168:169]
	v_lshl_add_u64 v[176:177], v[176:177], 0, v[0:1]
	v_cvt_pk_bf16_f32 v182, v182, v183
	v_cvt_pk_bf16_f32 v183, v186, v187
	v_cvt_pk_bf16_f32 v184, v184, v185
	v_cvt_pk_bf16_f32 v185, v190, v191
	global_store_dwordx4 v[176:177], v[182:185], off
	v_pk_mul_f32 v[188:189], v[76:77], s[0:1] op_sel_hi:[1,0]
	s_mov_b64 s[28:29], 0
	v_pk_mul_f32 v[182:183], v[82:83], s[0:1] op_sel_hi:[1,0]
	v_pk_mul_f32 v[184:185], v[80:81], s[0:1] op_sel_hi:[1,0]
	v_pk_mul_f32 v[186:187], v[182:183], v[164:165]
	v_pk_mul_f32 v[182:183], v[184:185], v[162:163]
	v_pk_mul_f32 v[184:185], v[78:79], s[0:1] op_sel_hi:[1,0]
	v_cvt_pk_bf16_f32 v182, v182, v183
	v_pk_mul_f32 v[190:191], v[184:185], v[156:157]
	v_pk_mul_f32 v[184:185], v[188:189], v[158:159]
	v_cvt_pk_bf16_f32 v183, v186, v187
	v_cvt_pk_bf16_f32 v184, v184, v185
	v_cvt_pk_bf16_f32 v185, v190, v191
	global_store_dwordx4 v[176:177], v[182:185], off offset:256

; __device__ __forceinline__ u32x4 pack8(f32x4 v0, f32x4 v1) { u32x4 w; w.x = cvt_pk_bf16(v0[0], v0[1]); w.y = cvt_pk_bf16(v0[2], v0[3]); w.z = cvt_pk_bf16(v1[0], v1[1]); w.w = cvt_pk_bf16(v1[2], v1[3]); return w; }
; __device__ __forceinline__ f32x4 dq4u8(unsigned w) { return (f32x4){(float)(w & 0xffu), (float)((w >> 8) & 0xffu), (float)((w >> 16) & 0xffu), (float)(w >> 24)}; }
;     __device__ __forceinline__ void operator()(f32x4 (&acc)[2][2][4][2], const Unit& u, int wr, int wc, int fr, int fq) const {
;     ...
;             for (int q = 0; q < 2; ++q) { const int m = 2 * mp2 + q; const size_t row = (size_t)(row0 + ai * HALF + m * 16); const unsigned char* gp = (const unsigned char*)G + row * 3072 + col0;
; #pragma unroll
;                 for (int bj = 0; bj < 2; ++bj) { ga[q][bj] = *(const u32x2q*)(gp + n * 1024 + bj * HALF); gb[q][bj] = *(const u32x2q*)(gp + nn * 1024 + bj * HALF); } }
;             asm volatile("" : "+v"(ga[0][0]), "+v"(ga[0][1]), "+v"(ga[1][0]), "+v"(ga[1][1]), "+v"(gb[0][0]), "+v"(gb[0][1]), "+v"(gb[1][0]), "+v"(gb[1][1]));
; #pragma unroll
;             for (int q = 0; q < 2; ++q) { const int m = 2 * mp2 + q; const size_t row = (size_t)(row0 + ai * HALF + m * 16);
;                 if (n < 2) {
; #pragma unroll
;                     for (int bj = 0; bj < 2; ++bj) { const f32x4 d0 = dq4u8(gb[q][bj].x), d1 = dq4u8(gb[q][bj].y);
;                         const f32x4 r0 = dq4u8(ga[q][bj].x) * (f32x4){__builtin_amdgcn_rcpf(d0[0]), __builtin_amdgcn_rcpf(d0[1]), __builtin_amdgcn_rcpf(d0[2]), __builtin_amdgcn_rcpf(d0[3])};
;                         const f32x4 r1 = dq4u8(ga[q][bj].y) * (f32x4){__builtin_amdgcn_rcpf(d1[0]), __builtin_amdgcn_rcpf(d1[1]), __builtin_amdgcn_rcpf(d1[2]), __builtin_amdgcn_rcpf(d1[3])};
;                         acc[ai][bj][m][0] *= r0; acc[ai][bj][m][1] *= r1; }
;                 } else { bf16_t* mp = MG + row * 1024 + col0;
; #pragma unroll
;                     for (int bj = 0; bj < 2; ++bj) *(u32x4*)(mp + bj * HALF) = pack8(dq4u8(ga[q][bj].x) * (acc[ai][bj][m][0] * (1.0f / 255.0f)), dq4u8(ga[q][bj].y) * (acc[ai][bj][m][1] * (1.0f / 255.0f))); } }
.LBB0_1057:
	v_add_u32_e32 v176, 0x80, v2
	v_mad_i64_i32 v[146:147], s[0:1], v176, s56, v[144:145]
	v_lshl_add_u64 v[148:149], v[146:147], 0, s[24:25]
	v_lshl_add_u64 v[146:147], v[146:147], 0, s[26:27]
	v_add_u32_e32 v150, 0x90, v2
	global_load_dwordx2 v[156:157], v[148:149], off nt
	global_load_dwordx2 v[170:171], v[146:147], off nt
	global_load_dwordx2 v[160:161], v[146:147], off offset:128 nt
	global_load_dwordx2 v[182:183], v[148:149], off offset:128 nt
	v_mad_i64_i32 v[146:147], s[0:1], v150, s56, v[144:145]
	v_lshl_add_u64 v[152:153], v[146:147], 0, s[24:25]
	v_lshl_add_u64 v[146:147], v[146:147], 0, s[26:27]
	global_load_dwordx2 v[154:155], v[152:153], off nt
	global_load_dwordx2 v[148:149], v[146:147], off nt
	s_nop 0
	global_load_dwordx2 v[146:147], v[146:147], off offset:128 nt
	s_nop 0
	global_load_dwordx2 v[152:153], v[152:153], off offset:128 nt
	s_mov_b64 s[28:29], -1
	s_and_b64 vcc, exec, s[6:7]
	s_waitcnt vmcnt(0)
	s_nop 0
	v_cvt_f32_ubyte1_e32 v173, v156
	v_cvt_f32_ubyte0_e32 v172, v156
	v_cvt_f32_ubyte3_e32 v175, v156
	v_cvt_f32_ubyte2_e32 v174, v156
	v_cvt_f32_ubyte1_e32 v169, v157
	v_cvt_f32_ubyte0_e32 v168, v157
	v_cvt_f32_ubyte3_e32 v167, v157
	v_cvt_f32_ubyte2_e32 v166, v157
	v_cvt_f32_ubyte1_e32 v163, v182
	v_cvt_f32_ubyte0_e32 v162, v182
	v_cvt_f32_ubyte3_e32 v165, v182
	v_cvt_f32_ubyte2_e32 v164, v182
	v_cvt_f32_ubyte1_e32 v159, v183
	v_cvt_f32_ubyte0_e32 v158, v183
	v_cvt_f32_ubyte3_e32 v157, v183
	v_cvt_f32_ubyte2_e32 v156, v183
	s_cbranch_vccnz .LBB0_1059
	s_mov_b32 s0, 0x3b808081
	v_ashrrev_i32_e32 v177, 31, v176
	v_pk_mul_f32 v[182:183], v[66:67], s[0:1] op_sel_hi:[1,0]
	v_pk_mul_f32 v[184:185], v[64:65], s[0:1] op_sel_hi:[1,0]
	v_lshlrev_b64 v[176:177], 11, v[176:177]
	v_pk_mul_f32 v[186:187], v[182:183], v[174:175]
	v_pk_mul_f32 v[182:183], v[184:185], v[172:173]
	v_pk_mul_f32 v[184:185], v[62:63], s[0:1] op_sel_hi:[1,0]
	v_pk_mul_f32 v[188:189], v[60:61], s[0:1] op_sel_hi:[1,0]
	v_lshl_add_u64 v[176:177], s[10:11], 0, v[176:177]
	v_pk_mul_f32 v[190:191], v[184:185], v[166:167]
	v_pk_mul_f32 v[184:185], v[188:189], v[168:169]
	v_lshl_add_u64 v[176:177], v[176:177], 0, v[0:1]
	v_cvt_pk_bf16_f32 v182, v182, v183
	v_cvt_pk_bf16_f32 v183, v186, v187
	v_cvt_pk_bf16_f32 v184, v184, v185
	v_cvt_pk_bf16_f32 v185, v190, v191
	global_store_dwordx4 v[176:177], v[182:185], off
	v_pk_mul_f32 v[188:189], v[28:29], s[0:1] op_sel_hi:[1,0]
	s_mov_b64 s[28:29], 0
	v_pk_mul_f32 v[182:183], v[34:35], s[0:1] op_sel_hi:[1,0]
	v_pk_mul_f32 v[184:185], v[32:33], s[0:1] op_sel_hi:[1,0]
	v_pk_mul_f32 v[186:187], v[182:183], v[164:165]
	v_pk_mul_f32 v[182:183], v[184:185], v[162:163]
	v_pk_mul_f32 v[184:185], v[30:31], s[0:1] op_sel_hi:[1,0]
	v_cvt_pk_bf16_f32 v182, v182, v183
	v_pk_mul_f32 v[190:191], v[184:185], v[156:157]
	v_pk_mul_f32 v[184:185], v[188:189], v[158:159]
	v_cvt_pk_bf16_f32 v183, v186, v187
	v_cvt_pk_bf16_f32 v184, v184, v185
	v_cvt_pk_bf16_f32 v185, v190, v191
	global_store_dwordx4 v[176:177], v[182:185], off offset:256

; __device__ __forceinline__ u32x4 pack8(f32x4 v0, f32x4 v1) { u32x4 w; w.x = cvt_pk_bf16(v0[0], v0[1]); w.y = cvt_pk_bf16(v0[2], v0[3]); w.z = cvt_pk_bf16(v1[0], v1[1]); w.w = cvt_pk_bf16(v1[2], v1[3]); return w; }
; __device__ __forceinline__ f32x4 dq4u8(unsigned w) { return (f32x4){(float)(w & 0xffu), (float)((w >> 8) & 0xffu), (float)((w >> 16) & 0xffu), (float)(w >> 24)}; }
;     __device__ __forceinline__ void operator()(f32x4 (&acc)[2][2][4][2], const Unit& u, int wr, int wc, int fr, int fq) const {
;     ...
;             for (int q = 0; q < 2; ++q) { const int m = 2 * mp2 + q; const size_t row = (size_t)(row0 + ai * HALF + m * 16); const unsigned char* gp = (const unsigned char*)G + row * 3072 + col0;
; #pragma unroll
;                 for (int bj = 0; bj < 2; ++bj) { ga[q][bj] = *(const u32x2q*)(gp + n * 1024 + bj * HALF); gb[q][bj] = *(const u32x2q*)(gp + nn * 1024 + bj * HALF); } }
;             asm volatile("" : "+v"(ga[0][0]), "+v"(ga[0][1]), "+v"(ga[1][0]), "+v"(ga[1][1]), "+v"(gb[0][0]), "+v"(gb[0][1]), "+v"(gb[1][0]), "+v"(gb[1][1]));
; #pragma unroll
;             for (int q = 0; q < 2; ++q) { const int m = 2 * mp2 + q; const size_t row = (size_t)(row0 + ai * HALF + m * 16);
;                 if (n < 2) {
; #pragma unroll
;                     for (int bj = 0; bj < 2; ++bj) { const f32x4 d0 = dq4u8(gb[q][bj].x), d1 = dq4u8(gb[q][bj].y);
;                         const f32x4 r0 = dq4u8(ga[q][bj].x) * (f32x4){__builtin_amdgcn_rcpf(d0[0]), __builtin_amdgcn_rcpf(d0[1]), __builtin_amdgcn_rcpf(d0[2]), __builtin_amdgcn_rcpf(d0[3])};
;                         const f32x4 r1 = dq4u8(ga[q][bj].y) * (f32x4){__builtin_amdgcn_rcpf(d1[0]), __builtin_amdgcn_rcpf(d1[1]), __builtin_amdgcn_rcpf(d1[2]), __builtin_amdgcn_rcpf(d1[3])};
;                         acc[ai][bj][m][0] *= r0; acc[ai][bj][m][1] *= r1; }
;                 } else { bf16_t* mp = MG + row * 1024 + col0;
; #pragma unroll
;                     for (int bj = 0; bj < 2; ++bj) *(u32x4*)(mp + bj * HALF) = pack8(dq4u8(ga[q][bj].x) * (acc[ai][bj][m][0] * (1.0f / 255.0f)), dq4u8(ga[q][bj].y) * (acc[ai][bj][m][1] * (1.0f / 255.0f))); } }
.LBB0_1065:
	v_add_u32_e32 v172, 0xa0, v2
	v_mad_i64_i32 v[146:147], s[0:1], v172, s56, v[144:145]
	v_lshl_add_u64 v[148:149], v[146:147], 0, s[24:25]
	v_lshl_add_u64 v[146:147], v[146:147], 0, s[26:27]
	global_load_dwordx2 v[152:153], v[148:149], off nt
	global_load_dwordx2 v[166:167], v[146:147], off nt
	global_load_dwordx2 v[156:157], v[146:147], off offset:128 nt
	global_load_dwordx2 v[174:175], v[148:149], off offset:128 nt
	v_add_u32_e32 v146, 0xb0, v2
	v_mad_i64_i32 v[2:3], s[0:1], v146, s56, v[144:145]
	v_lshl_add_u64 v[148:149], v[2:3], 0, s[24:25]
	v_lshl_add_u64 v[2:3], v[2:3], 0, s[26:27]
	global_load_dwordx2 v[150:151], v[148:149], off nt
	global_load_dwordx2 v[144:145], v[2:3], off nt
	s_nop 0
	global_load_dwordx2 v[2:3], v[2:3], off offset:128 nt
	s_nop 0
	global_load_dwordx2 v[148:149], v[148:149], off offset:128 nt
	s_mov_b64 s[24:25], -1
	s_and_b64 vcc, exec, s[6:7]
	s_waitcnt vmcnt(0)
	s_nop 0
	v_cvt_f32_ubyte1_e32 v169, v152
	v_cvt_f32_ubyte0_e32 v168, v152
	v_cvt_f32_ubyte3_e32 v171, v152
	v_cvt_f32_ubyte2_e32 v170, v152
	v_cvt_f32_ubyte1_e32 v165, v153
	v_cvt_f32_ubyte0_e32 v164, v153
	v_cvt_f32_ubyte3_e32 v163, v153
	v_cvt_f32_ubyte2_e32 v162, v153
	v_cvt_f32_ubyte1_e32 v159, v174
	v_cvt_f32_ubyte0_e32 v158, v174
	v_cvt_f32_ubyte3_e32 v161, v174
	v_cvt_f32_ubyte2_e32 v160, v174
	v_cvt_f32_ubyte1_e32 v155, v175
	v_cvt_f32_ubyte0_e32 v154, v175
	v_cvt_f32_ubyte3_e32 v153, v175
	v_cvt_f32_ubyte2_e32 v152, v175
	s_cbranch_vccnz .LBB0_1067
	v_ashrrev_i32_e32 v173, 31, v172
	v_lshlrev_b64 v[172:173], 11, v[172:173]
	v_lshl_add_u64 v[172:173], s[10:11], 0, v[172:173]
	s_mov_b32 s0, 0x3b808081
	v_lshl_add_u64 v[176:177], v[172:173], 0, v[0:1]
	v_pk_mul_f32 v[172:173], v[50:51], s[0:1] op_sel_hi:[1,0]
	v_pk_mul_f32 v[174:175], v[48:49], s[0:1] op_sel_hi:[1,0]
	v_pk_mul_f32 v[182:183], v[172:173], v[170:171]
	v_pk_mul_f32 v[172:173], v[174:175], v[168:169]
	v_pk_mul_f32 v[174:175], v[46:47], s[0:1] op_sel_hi:[1,0]
	v_pk_mul_f32 v[184:185], v[44:45], s[0:1] op_sel_hi:[1,0]
	v_pk_mul_f32 v[186:187], v[174:175], v[162:163]
	v_pk_mul_f32 v[174:175], v[184:185], v[164:165]
	v_cvt_pk_bf16_f32 v172, v172, v173
	v_cvt_pk_bf16_f32 v173, v182, v183
	v_cvt_pk_bf16_f32 v174, v174, v175
	v_cvt_pk_bf16_f32 v175, v186, v187
	global_store_dwordx4 v[176:177], v[172:175], off
	v_pk_mul_f32 v[184:185], v[12:13], s[0:1] op_sel_hi:[1,0]
	s_mov_b64 s[24:25], 0
	v_pk_mul_f32 v[172:173], v[18:19], s[0:1] op_sel_hi:[1,0]
	v_pk_mul_f32 v[174:175], v[16:17], s[0:1] op_sel_hi:[1,0]
	v_pk_mul_f32 v[182:183], v[172:173], v[160:161]
	v_pk_mul_f32 v[172:173], v[174:175], v[158:159]
	v_pk_mul_f32 v[174:175], v[14:15], s[0:1] op_sel_hi:[1,0]
	v_cvt_pk_bf16_f32 v172, v172, v173
	v_pk_mul_f32 v[186:187], v[174:175], v[152:153]
	v_pk_mul_f32 v[174:175], v[184:185], v[154:155]
	v_cvt_pk_bf16_f32 v173, v182, v183
	v_cvt_pk_bf16_f32 v174, v174, v175
	v_cvt_pk_bf16_f32 v175, v186, v187
	global_store_dwordx4 v[176:177], v[172:175], off offset:256
